# phase2: next tile query/weight rows prefetched during the selection; phase1 epilogue: redundant gain waits removed; phase6 epilogue rss loads batched
# speedup vs baseline: 1.0682x; 1.0189x over previous
; template <int AI>
; __device__ __forceinline__ void epi_inproj(const Params& p, const acc8_t& acc, int g, int tbase, int fr, int fq) {
;     ...
;     if (gain) {
;       float ss = 0.f;
; #pragma unroll
;       for (int k = 0; k < 16; k++) ss += x[k] * x[k];
;       ss = xsum16(ss);
;       ss = xsum32(ss);
;       const float rs = rsqrtf(ss * (1.f / 64.f) + 1e-6f);
; #pragma unroll
;       for (int bj = 0; bj < 2; bj++)
; #pragma unroll
;         for (int n = 0; n < 2; n++) {
;           x[(bj * 2 + n) * 4 + 0] *= rs * gg[bj][n].x; x[(bj * 2 + n) * 4 + 1] *= rs * gg[bj][n].y;
;           x[(bj * 2 + n) * 4 + 2] *= rs * gg[bj][n].z; x[(bj * 2 + n) * 4 + 3] *= rs * gg[bj][n].w;
;         }
;     }
.LBB0_304:
	s_and_b64 vcc, exec, s[10:11]
	s_cbranch_vccnz .LBB0_366
	v_mul_f32_e32 v114, v107, v107
	v_fmac_f32_e32 v114, v106, v106
	v_fmac_f32_e32 v114, v108, v108
	v_fmac_f32_e32 v114, v109, v109
	v_fmac_f32_e32 v114, v110, v110
	v_fmac_f32_e32 v114, v111, v111
	v_fmac_f32_e32 v114, v112, v112
	v_fmac_f32_e32 v114, v113, v113
	v_fmac_f32_e32 v114, v102, v102
	v_fmac_f32_e32 v114, v103, v103
	v_fmac_f32_e32 v114, v104, v104
	v_fmac_f32_e32 v114, v105, v105
	v_fmac_f32_e32 v114, v98, v98
	v_fmac_f32_e32 v114, v99, v99
	v_fmac_f32_e32 v114, v100, v100
	v_fmac_f32_e32 v114, v101, v101
	v_mov_b32_e32 v115, v114
	s_nop 1
	v_permlane16_swap_b32_e32 v114, v115
	v_add_f32_e32 v114, v114, v115
	v_mov_b32_e32 v115, v114
	s_nop 1
	v_permlane32_swap_b32_e32 v114, v115
	v_add_f32_e32 v114, v114, v115
	v_fmamk_f32 v114, v114, 0x3c800000, v191
	v_mul_f32_e32 v115, 0x4b800000, v114
	v_cmp_gt_f32_e32 vcc, s59, v114
	s_nop 1
	v_cndmask_b32_e32 v114, v114, v115, vcc
	v_rsq_f32_e32 v114, v114
	s_nop 0
	v_mul_f32_e32 v115, 0x45800000, v114
	v_cndmask_b32_e32 v114, v114, v115, vcc
	v_pk_mul_f32 v[122:123], v[130:131], v[114:115] op_sel_hi:[1,0]
	v_pk_mul_f32 v[116:117], v[132:133], v[114:115] op_sel_hi:[1,0]
	v_pk_mul_f32 v[124:125], v[134:135], v[114:115] op_sel_hi:[1,0]
	v_pk_mul_f32 v[126:127], v[136:137], v[114:115] op_sel_hi:[1,0]
	v_pk_mul_f32 v[128:129], v[138:139], v[114:115] op_sel_hi:[1,0]
	v_pk_mul_f32 v[146:147], v[140:141], v[114:115] op_sel_hi:[1,0]
	v_pk_mul_f32 v[148:149], v[142:143], v[114:115] op_sel_hi:[1,0]
	v_pk_mul_f32 v[114:115], v[144:145], v[114:115] op_sel_hi:[1,0]
	v_pk_mul_f32 v[98:99], v[98:99], v[148:149]
	v_pk_mul_f32 v[100:101], v[100:101], v[114:115]
	v_pk_mul_f32 v[104:105], v[104:105], v[146:147]
	v_pk_mul_f32 v[102:103], v[102:103], v[128:129]
	v_pk_mul_f32 v[112:113], v[112:113], v[126:127]
	v_pk_mul_f32 v[110:111], v[110:111], v[124:125]
	v_pk_mul_f32 v[116:117], v[108:109], v[116:117]
	v_pk_mul_f32 v[114:115], v[106:107], v[122:123]
	s_andn2_b64 vcc, exec, s[84:85]
	s_cbranch_vccnz .LBB0_307

; template <int AI>
; __device__ __forceinline__ void epi_inproj(const Params& p, const acc8_t& acc, int g, int tbase, int fr, int fq) {
;     ...
;     if (gain) {
;       float ss = 0.f;
; #pragma unroll
;       for (int k = 0; k < 16; k++) ss += x[k] * x[k];
;       ss = xsum16(ss);
;       ss = xsum32(ss);
;       const float rs = rsqrtf(ss * (1.f / 64.f) + 1e-6f);
; #pragma unroll
;       for (int bj = 0; bj < 2; bj++)
; #pragma unroll
;         for (int n = 0; n < 2; n++) {
;           x[(bj * 2 + n) * 4 + 0] *= rs * gg[bj][n].x; x[(bj * 2 + n) * 4 + 1] *= rs * gg[bj][n].y;
;           x[(bj * 2 + n) * 4 + 2] *= rs * gg[bj][n].z; x[(bj * 2 + n) * 4 + 3] *= rs * gg[bj][n].w;
;         }
;     }
.LBB0_318:
	s_and_b64 vcc, exec, s[10:11]
	s_cbranch_vccnz .LBB0_367
	v_mul_f32_e32 v98, v91, v91
	v_fmac_f32_e32 v98, v90, v90
	v_fmac_f32_e32 v98, v92, v92
	v_fmac_f32_e32 v98, v93, v93
	v_fmac_f32_e32 v98, v94, v94
	v_fmac_f32_e32 v98, v95, v95
	v_fmac_f32_e32 v98, v96, v96
	v_fmac_f32_e32 v98, v97, v97
	v_fmac_f32_e32 v98, v86, v86
	v_fmac_f32_e32 v98, v87, v87
	v_fmac_f32_e32 v98, v88, v88
	v_fmac_f32_e32 v98, v89, v89
	v_fmac_f32_e32 v98, v82, v82
	v_fmac_f32_e32 v98, v83, v83
	v_fmac_f32_e32 v98, v84, v84
	v_fmac_f32_e32 v98, v85, v85
	v_mov_b32_e32 v99, v98
	s_nop 1
	v_permlane16_swap_b32_e32 v98, v99
	v_add_f32_e32 v98, v98, v99
	v_mov_b32_e32 v99, v98
	s_nop 1
	v_permlane32_swap_b32_e32 v98, v99
	v_add_f32_e32 v98, v98, v99
	v_fmamk_f32 v98, v98, 0x3c800000, v191
	v_mul_f32_e32 v99, 0x4b800000, v98
	v_cmp_gt_f32_e32 vcc, s59, v98
	s_nop 1
	v_cndmask_b32_e32 v98, v98, v99, vcc
	v_rsq_f32_e32 v98, v98
	s_nop 0
	v_mul_f32_e32 v99, 0x45800000, v98
	v_cndmask_b32_e32 v98, v98, v99, vcc
	v_pk_mul_f32 v[104:105], v[130:131], v[98:99] op_sel_hi:[1,0]
	v_pk_mul_f32 v[100:101], v[132:133], v[98:99] op_sel_hi:[1,0]
	v_pk_mul_f32 v[106:107], v[134:135], v[98:99] op_sel_hi:[1,0]
	v_pk_mul_f32 v[108:109], v[136:137], v[98:99] op_sel_hi:[1,0]
	v_pk_mul_f32 v[110:111], v[138:139], v[98:99] op_sel_hi:[1,0]
	v_pk_mul_f32 v[112:113], v[140:141], v[98:99] op_sel_hi:[1,0]
	v_pk_mul_f32 v[114:115], v[142:143], v[98:99] op_sel_hi:[1,0]
	v_pk_mul_f32 v[98:99], v[144:145], v[98:99] op_sel_hi:[1,0]
	v_pk_mul_f32 v[82:83], v[82:83], v[114:115]
	v_pk_mul_f32 v[84:85], v[84:85], v[98:99]
	v_pk_mul_f32 v[88:89], v[88:89], v[112:113]
	v_pk_mul_f32 v[86:87], v[86:87], v[110:111]
	v_pk_mul_f32 v[96:97], v[96:97], v[108:109]
	v_pk_mul_f32 v[94:95], v[94:95], v[106:107]
	v_pk_mul_f32 v[100:101], v[92:93], v[100:101]
	v_pk_mul_f32 v[98:99], v[90:91], v[104:105]
	s_andn2_b64 vcc, exec, s[84:85]
	s_cbranch_vccnz .LBB0_321

; template <int AI>
; __device__ __forceinline__ void epi_inproj(const Params& p, const acc8_t& acc, int g, int tbase, int fr, int fq) {
;     ...
;     if (gain) {
;       float ss = 0.f;
; #pragma unroll
;       for (int k = 0; k < 16; k++) ss += x[k] * x[k];
;       ss = xsum16(ss);
;       ss = xsum32(ss);
;       const float rs = rsqrtf(ss * (1.f / 64.f) + 1e-6f);
; #pragma unroll
;       for (int bj = 0; bj < 2; bj++)
; #pragma unroll
;         for (int n = 0; n < 2; n++) {
;           x[(bj * 2 + n) * 4 + 0] *= rs * gg[bj][n].x; x[(bj * 2 + n) * 4 + 1] *= rs * gg[bj][n].y;
;           x[(bj * 2 + n) * 4 + 2] *= rs * gg[bj][n].z; x[(bj * 2 + n) * 4 + 3] *= rs * gg[bj][n].w;
;         }
;     }
.LBB0_332:
	s_and_b64 vcc, exec, s[10:11]
	s_cbranch_vccnz .LBB0_368
	v_mul_f32_e32 v82, v75, v75
	v_fmac_f32_e32 v82, v74, v74
	v_fmac_f32_e32 v82, v76, v76
	v_fmac_f32_e32 v82, v77, v77
	v_fmac_f32_e32 v82, v78, v78
	v_fmac_f32_e32 v82, v79, v79
	v_fmac_f32_e32 v82, v80, v80
	v_fmac_f32_e32 v82, v81, v81
	v_fmac_f32_e32 v82, v70, v70
	v_fmac_f32_e32 v82, v71, v71
	v_fmac_f32_e32 v82, v72, v72
	v_fmac_f32_e32 v82, v73, v73
	v_fmac_f32_e32 v82, v66, v66
	v_fmac_f32_e32 v82, v67, v67
	v_fmac_f32_e32 v82, v68, v68
	v_fmac_f32_e32 v82, v69, v69
	v_mov_b32_e32 v83, v82
	s_nop 1
	v_permlane16_swap_b32_e32 v82, v83
	v_add_f32_e32 v82, v82, v83
	v_mov_b32_e32 v83, v82
	s_nop 1
	v_permlane32_swap_b32_e32 v82, v83
	v_add_f32_e32 v82, v82, v83
	v_fmamk_f32 v82, v82, 0x3c800000, v191
	v_mul_f32_e32 v83, 0x4b800000, v82
	v_cmp_gt_f32_e32 vcc, s59, v82
	s_nop 1
	v_cndmask_b32_e32 v82, v82, v83, vcc
	v_rsq_f32_e32 v82, v82
	s_nop 0
	v_mul_f32_e32 v83, 0x45800000, v82
	v_cndmask_b32_e32 v82, v82, v83, vcc
	v_pk_mul_f32 v[88:89], v[130:131], v[82:83] op_sel_hi:[1,0]
	v_pk_mul_f32 v[84:85], v[132:133], v[82:83] op_sel_hi:[1,0]
	v_pk_mul_f32 v[90:91], v[134:135], v[82:83] op_sel_hi:[1,0]
	v_pk_mul_f32 v[92:93], v[136:137], v[82:83] op_sel_hi:[1,0]
	v_pk_mul_f32 v[94:95], v[138:139], v[82:83] op_sel_hi:[1,0]
	v_pk_mul_f32 v[96:97], v[140:141], v[82:83] op_sel_hi:[1,0]
	v_pk_mul_f32 v[98:99], v[142:143], v[82:83] op_sel_hi:[1,0]
	v_pk_mul_f32 v[82:83], v[144:145], v[82:83] op_sel_hi:[1,0]
	v_pk_mul_f32 v[66:67], v[66:67], v[98:99]
	v_pk_mul_f32 v[68:69], v[68:69], v[82:83]
	v_pk_mul_f32 v[72:73], v[72:73], v[96:97]
	v_pk_mul_f32 v[70:71], v[70:71], v[94:95]
	v_pk_mul_f32 v[80:81], v[80:81], v[92:93]
	v_pk_mul_f32 v[78:79], v[78:79], v[90:91]
	v_pk_mul_f32 v[84:85], v[76:77], v[84:85]
	v_pk_mul_f32 v[82:83], v[74:75], v[88:89]
	s_andn2_b64 vcc, exec, s[84:85]
	s_cbranch_vccnz .LBB0_335

; template <int AI>
; __device__ __forceinline__ void epi_inproj(const Params& p, const acc8_t& acc, int g, int tbase, int fr, int fq) {
;     ...
;     if (gain) {
;       float ss = 0.f;
; #pragma unroll
;       for (int k = 0; k < 16; k++) ss += x[k] * x[k];
;       ss = xsum16(ss);
;       ss = xsum32(ss);
;       const float rs = rsqrtf(ss * (1.f / 64.f) + 1e-6f);
; #pragma unroll
;       for (int bj = 0; bj < 2; bj++)
; #pragma unroll
;         for (int n = 0; n < 2; n++) {
;           x[(bj * 2 + n) * 4 + 0] *= rs * gg[bj][n].x; x[(bj * 2 + n) * 4 + 1] *= rs * gg[bj][n].y;
;           x[(bj * 2 + n) * 4 + 2] *= rs * gg[bj][n].z; x[(bj * 2 + n) * 4 + 3] *= rs * gg[bj][n].w;
;         }
;     }
.LBB0_415:
	s_and_b64 vcc, exec, s[10:11]
	s_cbranch_vccnz .LBB0_462
	v_mul_f32_e32 v50, v43, v43
	v_fmac_f32_e32 v50, v42, v42
	v_fmac_f32_e32 v50, v44, v44
	v_fmac_f32_e32 v50, v45, v45
	v_fmac_f32_e32 v50, v46, v46
	v_fmac_f32_e32 v50, v47, v47
	v_fmac_f32_e32 v50, v48, v48
	v_fmac_f32_e32 v50, v49, v49
	v_fmac_f32_e32 v50, v38, v38
	v_fmac_f32_e32 v50, v39, v39
	v_fmac_f32_e32 v50, v40, v40
	v_fmac_f32_e32 v50, v41, v41
	v_fmac_f32_e32 v50, v34, v34
	v_fmac_f32_e32 v50, v35, v35
	v_fmac_f32_e32 v50, v36, v36
	v_fmac_f32_e32 v50, v37, v37
	v_mov_b32_e32 v51, v50
	s_nop 1
	v_permlane16_swap_b32_e32 v50, v51
	v_add_f32_e32 v50, v50, v51
	v_mov_b32_e32 v51, v50
	s_nop 1
	v_permlane32_swap_b32_e32 v50, v51
	v_add_f32_e32 v50, v50, v51
	v_fmamk_f32 v50, v50, 0x3c800000, v191
	v_mul_f32_e32 v51, 0x4b800000, v50
	v_cmp_gt_f32_e32 vcc, s59, v50
	s_nop 1
	v_cndmask_b32_e32 v50, v50, v51, vcc
	v_rsq_f32_e32 v50, v50
	s_nop 0
	v_mul_f32_e32 v51, 0x45800000, v50
	v_cndmask_b32_e32 v50, v50, v51, vcc
	v_pk_mul_f32 v[58:59], v[66:67], v[50:51] op_sel_hi:[1,0]
	v_pk_mul_f32 v[52:53], v[68:69], v[50:51] op_sel_hi:[1,0]
	v_pk_mul_f32 v[60:61], v[70:71], v[50:51] op_sel_hi:[1,0]
	v_pk_mul_f32 v[62:63], v[72:73], v[50:51] op_sel_hi:[1,0]
	v_pk_mul_f32 v[64:65], v[74:75], v[50:51] op_sel_hi:[1,0]
	v_pk_mul_f32 v[82:83], v[76:77], v[50:51] op_sel_hi:[1,0]
	v_pk_mul_f32 v[84:85], v[78:79], v[50:51] op_sel_hi:[1,0]
	v_pk_mul_f32 v[50:51], v[80:81], v[50:51] op_sel_hi:[1,0]
	v_pk_mul_f32 v[34:35], v[34:35], v[84:85]
	v_pk_mul_f32 v[36:37], v[36:37], v[50:51]
	v_pk_mul_f32 v[40:41], v[40:41], v[82:83]
	v_pk_mul_f32 v[38:39], v[38:39], v[64:65]
	v_pk_mul_f32 v[48:49], v[48:49], v[62:63]
	v_pk_mul_f32 v[46:47], v[46:47], v[60:61]
	v_pk_mul_f32 v[52:53], v[44:45], v[52:53]
	v_pk_mul_f32 v[50:51], v[42:43], v[58:59]
	s_andn2_b64 vcc, exec, s[82:83]
	s_cbranch_vccnz .LBB0_418

; template <int AI>
; __device__ __forceinline__ void epi_inproj(const Params& p, const acc8_t& acc, int g, int tbase, int fr, int fq) {
;     ...
;     if (gain) {
;       float ss = 0.f;
; #pragma unroll
;       for (int k = 0; k < 16; k++) ss += x[k] * x[k];
;       ss = xsum16(ss);
;       ss = xsum32(ss);
;       const float rs = rsqrtf(ss * (1.f / 64.f) + 1e-6f);
; #pragma unroll
;       for (int bj = 0; bj < 2; bj++)
; #pragma unroll
;         for (int n = 0; n < 2; n++) {
;           x[(bj * 2 + n) * 4 + 0] *= rs * gg[bj][n].x; x[(bj * 2 + n) * 4 + 1] *= rs * gg[bj][n].y;
;           x[(bj * 2 + n) * 4 + 2] *= rs * gg[bj][n].z; x[(bj * 2 + n) * 4 + 3] *= rs * gg[bj][n].w;
;         }
;     }
.LBB0_429:
	s_and_b64 vcc, exec, s[10:11]
	s_cbranch_vccnz .LBB0_463
	v_mul_f32_e32 v34, v27, v27
	v_fmac_f32_e32 v34, v26, v26
	v_fmac_f32_e32 v34, v28, v28
	v_fmac_f32_e32 v34, v29, v29
	v_fmac_f32_e32 v34, v30, v30
	v_fmac_f32_e32 v34, v31, v31
	v_fmac_f32_e32 v34, v32, v32
	v_fmac_f32_e32 v34, v33, v33
	v_fmac_f32_e32 v34, v22, v22
	v_fmac_f32_e32 v34, v23, v23
	v_fmac_f32_e32 v34, v24, v24
	v_fmac_f32_e32 v34, v25, v25
	v_fmac_f32_e32 v34, v18, v18
	v_fmac_f32_e32 v34, v19, v19
	v_fmac_f32_e32 v34, v20, v20
	v_fmac_f32_e32 v34, v21, v21
	v_mov_b32_e32 v35, v34
	s_nop 1
	v_permlane16_swap_b32_e32 v34, v35
	v_add_f32_e32 v34, v34, v35
	v_mov_b32_e32 v35, v34
	s_nop 1
	v_permlane32_swap_b32_e32 v34, v35
	v_add_f32_e32 v34, v34, v35
	v_fmamk_f32 v34, v34, 0x3c800000, v191
	v_mul_f32_e32 v35, 0x4b800000, v34
	v_cmp_gt_f32_e32 vcc, s59, v34
	s_nop 1
	v_cndmask_b32_e32 v34, v34, v35, vcc
	v_rsq_f32_e32 v34, v34
	s_nop 0
	v_mul_f32_e32 v35, 0x45800000, v34
	v_cndmask_b32_e32 v34, v34, v35, vcc
	v_pk_mul_f32 v[40:41], v[66:67], v[34:35] op_sel_hi:[1,0]
	v_pk_mul_f32 v[36:37], v[68:69], v[34:35] op_sel_hi:[1,0]
	v_pk_mul_f32 v[42:43], v[70:71], v[34:35] op_sel_hi:[1,0]
	v_pk_mul_f32 v[44:45], v[72:73], v[34:35] op_sel_hi:[1,0]
	v_pk_mul_f32 v[46:47], v[74:75], v[34:35] op_sel_hi:[1,0]
	v_pk_mul_f32 v[48:49], v[76:77], v[34:35] op_sel_hi:[1,0]
	v_pk_mul_f32 v[50:51], v[78:79], v[34:35] op_sel_hi:[1,0]
	v_pk_mul_f32 v[34:35], v[80:81], v[34:35] op_sel_hi:[1,0]
	v_pk_mul_f32 v[18:19], v[18:19], v[50:51]
	v_pk_mul_f32 v[20:21], v[20:21], v[34:35]
	v_pk_mul_f32 v[24:25], v[24:25], v[48:49]
	v_pk_mul_f32 v[22:23], v[22:23], v[46:47]
	v_pk_mul_f32 v[32:33], v[32:33], v[44:45]
	v_pk_mul_f32 v[30:31], v[30:31], v[42:43]
	v_pk_mul_f32 v[36:37], v[28:29], v[36:37]
	v_pk_mul_f32 v[34:35], v[26:27], v[40:41]
	s_andn2_b64 vcc, exec, s[82:83]
	s_cbranch_vccnz .LBB0_432

; template <int AI>
; __device__ __forceinline__ void epi_inproj(const Params& p, const acc8_t& acc, int g, int tbase, int fr, int fq) {
;     ...
;     if (gain) {
;       float ss = 0.f;
; #pragma unroll
;       for (int k = 0; k < 16; k++) ss += x[k] * x[k];
;       ss = xsum16(ss);
;       ss = xsum32(ss);
;       const float rs = rsqrtf(ss * (1.f / 64.f) + 1e-6f);
; #pragma unroll
;       for (int bj = 0; bj < 2; bj++)
; #pragma unroll
;         for (int n = 0; n < 2; n++) {
;           x[(bj * 2 + n) * 4 + 0] *= rs * gg[bj][n].x; x[(bj * 2 + n) * 4 + 1] *= rs * gg[bj][n].y;
;           x[(bj * 2 + n) * 4 + 2] *= rs * gg[bj][n].z; x[(bj * 2 + n) * 4 + 3] *= rs * gg[bj][n].w;
;         }
;     }
.LBB0_443:
	s_and_b64 vcc, exec, s[10:11]
	s_cbranch_vccnz .LBB0_464
	v_mul_f32_e32 v18, v7, v7
	v_fmac_f32_e32 v18, v6, v6
	v_fmac_f32_e32 v18, v8, v8
	v_fmac_f32_e32 v18, v9, v9
	v_fmac_f32_e32 v18, v14, v14
	v_fmac_f32_e32 v18, v15, v15
	v_fmac_f32_e32 v18, v16, v16
	v_fmac_f32_e32 v18, v17, v17
	v_fmac_f32_e32 v18, v10, v10
	v_fmac_f32_e32 v18, v11, v11
	v_fmac_f32_e32 v18, v12, v12
	v_fmac_f32_e32 v18, v13, v13
	v_fmac_f32_e32 v18, v2, v2
	v_fmac_f32_e32 v18, v3, v3
	v_fmac_f32_e32 v18, v4, v4
	v_fmac_f32_e32 v18, v5, v5
	v_mov_b32_e32 v19, v18
	s_nop 1
	v_permlane16_swap_b32_e32 v18, v19
	v_add_f32_e32 v18, v18, v19
	v_mov_b32_e32 v19, v18
	s_nop 1
	v_permlane32_swap_b32_e32 v18, v19
	v_add_f32_e32 v18, v18, v19
	v_fmamk_f32 v18, v18, 0x3c800000, v191
	v_mul_f32_e32 v19, 0x4b800000, v18
	v_cmp_gt_f32_e32 vcc, s59, v18
	s_nop 1
	v_cndmask_b32_e32 v18, v18, v19, vcc
	v_rsq_f32_e32 v18, v18
	s_nop 0
	v_mul_f32_e32 v19, 0x45800000, v18
	v_cndmask_b32_e32 v18, v18, v19, vcc
	v_pk_mul_f32 v[24:25], v[66:67], v[18:19] op_sel_hi:[1,0]
	v_pk_mul_f32 v[20:21], v[68:69], v[18:19] op_sel_hi:[1,0]
	v_pk_mul_f32 v[26:27], v[70:71], v[18:19] op_sel_hi:[1,0]
	v_pk_mul_f32 v[28:29], v[72:73], v[18:19] op_sel_hi:[1,0]
	v_pk_mul_f32 v[30:31], v[74:75], v[18:19] op_sel_hi:[1,0]
	v_pk_mul_f32 v[32:33], v[76:77], v[18:19] op_sel_hi:[1,0]
	v_pk_mul_f32 v[34:35], v[78:79], v[18:19] op_sel_hi:[1,0]
	v_pk_mul_f32 v[18:19], v[80:81], v[18:19] op_sel_hi:[1,0]
	v_pk_mul_f32 v[2:3], v[2:3], v[34:35]
	v_pk_mul_f32 v[4:5], v[4:5], v[18:19]
	v_pk_mul_f32 v[12:13], v[12:13], v[32:33]
	v_pk_mul_f32 v[10:11], v[10:11], v[30:31]
	v_pk_mul_f32 v[16:17], v[16:17], v[28:29]
	v_pk_mul_f32 v[14:15], v[14:15], v[26:27]
	v_pk_mul_f32 v[20:21], v[8:9], v[20:21]
	v_pk_mul_f32 v[18:19], v[6:7], v[24:25]
	s_andn2_b64 vcc, exec, s[82:83]
	s_cbranch_vccnz .LBB0_446

; __device__ void phase2(const Params& p, unsigned char* smem) {
;   u16 (*sc)[8192] = (u16 (*)[8192])smem;
;   unsigned char* ws = p.ws;
;   const int tid = threadIdx.x, lane = tid & 63, wave = tid >> 6;
;   const int NTILE = 4096 + 64;
;   for (int it = blockIdx.x; it < NTILE; it += gridDim.x) {
;     const int rr = it >> 8, ww = it & 255;
;     const int idx = (rr & 1) ? (rr << 8) + 255 - ww : it;
;     int tok0, nvis; const u16* KI; u64* mrow0; int mld;
;     if (idx < 4096) {
;       int b = idx & 3, j8 = 1023 - (idx >> 2);
;       int q0 = j8 * 8;
;       tok0 = b * 8192 + q0; nvis = ((q0 >> 6) + 1) * 64;
;       KI = (const u16*)(ws + OFF_KIP) + (size_t)b * 8192 * 64;
;       mrow0 = (u64*)(ws + OFF_MASKP) + (size_t)tok0 * 128; mld = 128;
;     } else {
;       int s = idx - 4096; int b = s >> 3, q0 = (s & 7) * 8;
;       tok0 = NPROMPT + b * 64 + q0; nvis = 1088;
;       KI = (const u16*)(ws + OFF_KIS) + (size_t)b * 1088 * 64;
;       mrow0 = (u64*)(ws + OFF_MASKS) + (size_t)(b * 64 + q0) * 32; mld = 32;
;     }
;     const int nv512 = (nvis + 511) >> 9;
;     {
;       const int tail = nv512 * 512 - nvis;
;       for (int e = tid; e < 8 * tail; e += 512) { int q = e / tail, k = e % tail; sc[q][nvis + k] = 0; }
;     }
;     const u16* QI = (const u16*)(ws + OFF_QI);
;     const float* WI = (const float*)(ws + OFF_WI);
;     const int n16 = lane & 15, g4 = lane >> 4;
.LBB0_524:
	s_cmp_gt_i32 s90, 2
	s_cselect_b64 s[0:1], -1, 0
	s_cmp_lt_i32 s91, 2
	s_cselect_b64 s[4:5], -1, 0
	s_or_b64 s[0:1], s[0:1], s[4:5]
	s_and_b64 vcc, exec, s[0:1]
	s_cbranch_vccnz .LBB0_608
	s_cmpk_gt_i32 s94, 0x103f
	v_and_b32_e32 v2, 0x3ff, v0
	s_cbranch_scc1 .LBB0_596
	v_lshlrev_b32_e32 v1, 7, v2
	s_waitcnt vmcnt(0)
	v_lshrrev_b32_e32 v133, 6, v2
	v_and_b32_e32 v118, 0x380, v1
	v_mov_b32_e32 v119, 0
	s_add_u32 s0, s88, 0x19aa4800
	v_and_b32_e32 v9, 15, v2
	v_lshl_add_u64 v[4:5], s[88:89], 0, v[118:119]
	v_and_b32_e32 v118, 48, v2
	v_bfe_u32 v145, v2, 5, 1
	v_lshlrev_b32_e32 v11, 7, v133
	s_addc_u32 s1, s89, 0
	v_lshrrev_b32_e32 v1, 1, v2
	v_lshl_add_u64 v[4:5], v[4:5], 0, v[118:119]
	s_mov_b64 s[6:7], 0xa220800
	v_lshl_or_b32 v11, v145, 14, v11
	v_lshlrev_b32_e32 v12, 1, v9
	s_mov_b32 s37, 0x10000
	v_and_b32_e32 v7, 63, v2
	s_add_u32 s3, s88, 0x196a4800
	v_and_b32_e32 v6, 24, v1
	v_lshl_add_u64 v[120:121], v[4:5], 0, s[6:7]
	v_and_b32_e32 v4, 16, v2
	v_mov_b32_e32 v5, v119
	v_lshlrev_b32_e32 v8, 6, v9
	v_mov_b32_e32 v1, 0x20000
	v_or3_b32 v151, v11, v12, s37
	v_lshlrev_b32_e32 v11, 13, v133
	v_lshlrev_b32_e32 v9, 7, v9
	s_addc_u32 s33, s89, 0
	v_lshl_add_u64 v[4:5], s[88:89], 0, v[4:5]
	s_mov_b64 s[6:7], 0x144a0800
	v_lshl_or_b32 v147, v133, 10, v1
	v_lshlrev_b32_e32 v149, 4, v7
	v_or3_b32 v118, v11, v9, v118
	s_mov_b64 s[60:61], 0x10000
	v_lshlrev_b32_e32 v138, 1, v6
	v_mbcnt_lo_u32_b32 v6, -1, 0
	s_mov_b64 s[4:5], src_shared_base
	v_lshl_add_u64 v[122:123], v[4:5], 0, s[6:7]
	v_lshlrev_b32_e32 v10, 12, v133
	v_lshlrev_b32_e32 v146, 14, v133
	v_or_b32_e32 v124, v147, v149
	v_lshlrev_b64 v[4:5], v2, -1
	s_add_u32 s56, s92, 0xc0
	s_movk_i32 s36, 0x400
	v_lshl_add_u64 v[134:135], v[118:119], 0, s[60:61]
	v_lshlrev_b32_e32 v118, 3, v7
	v_mbcnt_hi_u32_b32 v154, -1, v6
	v_mov_b32_e32 v6, 0x80
	v_bfe_u32 v144, v2, 3, 1
	v_lshlrev_b32_e32 v148, 2, v7
	v_mov_b32_e32 v125, s5
	v_or_b32_e32 v126, 4, v124
	v_mov_b32_e32 v127, s5
	v_or_b32_e32 v128, 8, v124
	v_mov_b32_e32 v129, s5
	v_or_b32_e32 v130, 12, v124
	v_mov_b32_e32 v131, s5
	v_not_b32_e32 v1, v5
	v_not_b32_e32 v132, v4
	v_cmp_gt_u32_e64 s[4:5], 8, v7
	s_addc_u32 s57, s93, 0
	v_cmp_eq_u32_e64 s[6:7], 63, v7
	v_cmp_gt_u32_e64 s[8:9], 62, v7
	v_cmp_gt_u32_e64 s[10:11], 60, v7
	v_cmp_gt_u32_e64 s[12:13], 56, v7
	v_cmp_gt_u32_e64 s[14:15], 48, v7
	v_cmp_gt_u32_e64 s[16:17], 32, v7
	s_mov_b32 s59, 0
	v_cmp_eq_u32_e64 s[18:19], 0, v7
	v_cmp_eq_u32_e64 s[20:21], 1, v7
	v_cmp_eq_u32_e64 s[22:23], 2, v7
	v_cmp_eq_u32_e64 s[24:25], 3, v7
	v_cmp_eq_u32_e64 s[26:27], 4, v7
	v_cmp_eq_u32_e64 s[28:29], 5, v7
	v_cmp_eq_u32_e64 s[30:31], 6, v7
	v_cmp_eq_u32_e64 s[34:35], 7, v7
	v_not_b32_e32 v150, v2
	v_add_u32_e32 v5, 0x600, v2
	v_or_b32_e32 v4, 0x400, v2
	v_add_u32_e32 v3, 0x200, v2
	v_or3_b32 v152, v146, v149, s36
	v_lshl_add_u64 v[136:137], s[88:89], 0, v[118:119]
	s_movk_i32 s68, 0x100
	s_movk_i32 s69, 0xff
	s_movk_i32 s70, 0x5ff
	v_lshlrev_b32_e32 v118, 1, v8
	v_lshlrev_b32_e32 v140, 1, v10
	s_movk_i32 s71, 0x8000
	v_mov_b32_e32 v153, 1
	v_mov_b32_e32 v156, v119
	v_mov_b32_e32 v157, v119
	v_mov_b32_e32 v158, v119
	v_mov_b32_e32 v159, v119
	v_lshl_or_b32 v155, v154, 2, v6
	s_mov_b32 s72, s94
	s_mov_b32 s97, 0
	s_branch .LBB0_528

; __device__ void phase2(const Params& p, unsigned char* smem) {
;     ...
;     const int nv512 = (nvis + 511) >> 9;
;     {
;       const int tail = nv512 * 512 - nvis;
;       for (int e = tid; e < 8 * tail; e += 512) { int q = e / tail, k = e % tail; sc[q][nvis + k] = 0; }
;     }
;     const u16* QI = (const u16*)(ws + OFF_QI);
;     const float* WI = (const float*)(ws + OFF_WI);
;     const int n16 = lane & 15, g4 = lane >> 4;
;     bf16x8 qa[4][2]; float4 wv[4];
; #pragma unroll
;     for (int pp = 0; pp < 4; pp++) {
;       const int ql = 2 * pp + (n16 >> 3), hh = n16 & 7;
; #pragma unroll
;       for (int kh = 0; kh < 2; kh++)
;         qa[pp][kh] = as_bf8(*(const uint4*)(QI + (size_t)(tok0 + ql) * 512 + hh * 64 + kh * 32 + 8 * g4));
;       wv[pp] = *(const float4*)(WI + (size_t)(tok0 + 2 * pp + (g4 >> 1)) * 8 + 4 * (g4 & 1));
;     }
;     {
;       const int nchunk = nvis >> 6;
;       const u16* kbase = KI + (size_t)n16 * 64 + 8 * g4;
;       bf16x8 nA0, nB0, nA1, nB1, nA2, nB2, nA3, nB3;
;       int c = wave;
;       if (c < nchunk) P2_LOADCHUNK(c, nA0, nB0, nA1, nB1, nA2, nB2, nA3, nB3)
.LBB0_533:
	s_add_i32 s45, s74, 0x1ff
	s_and_b32 s36, s45, 0xfffffe00
	s_sub_i32 s76, s36, s74
	s_lshl_b32 s47, s76, 3
	s_lshr_b32 s73, s45, 9
	s_cmp_lg_u32 s97, 0
	s_cbranch_scc1 .Lq_skip
	v_add_u32_e32 v70, s75, v144
	v_add_u32_e32 v78, s75, v145
	v_ashrrev_i32_e32 v71, 31, v70
	v_ashrrev_i32_e32 v79, 31, v78
	v_lshlrev_b64 v[38:39], 10, v[70:71]
	v_lshlrev_b64 v[46:47], 5, v[78:79]
	v_add_u32_e32 v48, 2, v70
	v_add_u32_e32 v56, 2, v78
	v_add_u32_e32 v62, 4, v70
	v_add_u32_e32 v72, 4, v78
	v_add_u32_e32 v70, 6, v70
	v_add_u32_e32 v78, 6, v78
	v_ashrrev_i32_e32 v49, 31, v48
	v_ashrrev_i32_e32 v57, 31, v56
	v_ashrrev_i32_e32 v63, 31, v62
	v_ashrrev_i32_e32 v73, 31, v72
	v_ashrrev_i32_e32 v71, 31, v70
	v_ashrrev_i32_e32 v79, 31, v78
	v_lshlrev_b64 v[48:49], 10, v[48:49]
	v_lshlrev_b64 v[56:57], 5, v[56:57]
	v_lshlrev_b64 v[62:63], 10, v[62:63]
	v_lshlrev_b64 v[72:73], 5, v[72:73]
	v_lshlrev_b64 v[70:71], 10, v[70:71]
	v_lshlrev_b64 v[78:79], 5, v[78:79]
	v_lshl_add_u64 v[42:43], v[120:121], 0, v[38:39]
	v_lshl_add_u64 v[46:47], v[122:123], 0, v[46:47]
	v_lshl_add_u64 v[54:55], v[120:121], 0, v[48:49]
	v_lshl_add_u64 v[58:59], v[122:123], 0, v[56:57]
	v_lshl_add_u64 v[66:67], v[120:121], 0, v[62:63]
	v_lshl_add_u64 v[72:73], v[122:123], 0, v[72:73]
	v_lshl_add_u64 v[80:81], v[120:121], 0, v[70:71]
	v_lshl_add_u64 v[82:83], v[122:123], 0, v[78:79]
	global_load_dwordx4 v[38:41], v[42:43], off
	s_nop 0
	global_load_dwordx4 v[42:45], v[42:43], off offset:64
	s_nop 0
	global_load_dwordx4 v[46:49], v[46:47], off
	s_nop 0
	global_load_dwordx4 v[50:53], v[54:55], off
	s_nop 0
	global_load_dwordx4 v[54:57], v[54:55], off offset:64
	s_nop 0
	global_load_dwordx4 v[58:61], v[58:59], off
	s_nop 0
	global_load_dwordx4 v[62:65], v[66:67], off
	s_nop 0
	global_load_dwordx4 v[66:69], v[66:67], off offset:64
	s_nop 0
	global_load_dwordx4 v[70:73], v[72:73], off
	s_nop 0
	global_load_dwordx4 v[74:77], v[80:81], off
	s_nop 0
	global_load_dwordx4 v[78:81], v[80:81], off offset:64
	s_nop 0
	global_load_dwordx4 v[82:85], v[82:83], off
.Lq_skip:
	s_lshr_b32 s47, s74, 6
	v_cmp_gt_u32_e64 s[36:37], s47, v133
	s_and_saveexec_b64 s[38:39], s[36:37]
	s_cbranch_execz .LBB0_548
	v_lshl_add_u64 v[6:7], s[48:49], 0, v[118:119]
	v_mov_b32_e32 v139, v119
	v_lshl_add_u64 v[6:7], v[6:7], 0, v[138:139]
	v_mov_b32_e32 v141, v119
	v_lshl_add_u64 v[6:7], v[6:7], 0, v[140:141]
	global_load_dwordx4 v[34:37], v[6:7], off
	global_load_dwordx4 v[30:33], v[6:7], off offset:64
	global_load_dwordx4 v[26:29], v[6:7], off offset:2048
	global_load_dwordx4 v[22:25], v[6:7], off offset:2112
	v_add_co_u32_e32 v6, vcc, 0x1000, v6
	s_nop 1
	v_addc_co_u32_e32 v7, vcc, 0, v7, vcc
	global_load_dwordx4 v[18:21], v[6:7], off
	global_load_dwordx4 v[14:17], v[6:7], off offset:64
	global_load_dwordx4 v[10:13], v[6:7], off offset:2048
	s_nop 0
	global_load_dwordx4 v[6:9], v[6:7], off offset:2112

; __device__ void phase2(const Params& p, unsigned char* smem) {
;     ...
;   for (int it = blockIdx.x; it < NTILE; it += gridDim.x) {
;     const int rr = it >> 8, ww = it & 255;
;     const int idx = (rr & 1) ? (rr << 8) + 255 - ww : it;
;     int tok0, nvis; const u16* KI; u64* mrow0; int mld;
;     if (idx < 4096) {
;       int b = idx & 3, j8 = 1023 - (idx >> 2);
;       int q0 = j8 * 8;
;       tok0 = b * 8192 + q0; nvis = ((q0 >> 6) + 1) * 64;
;       KI = (const u16*)(ws + OFF_KIP) + (size_t)b * 8192 * 64;
;       mrow0 = (u64*)(ws + OFF_MASKP) + (size_t)tok0 * 128; mld = 128;
;     } else {
;       int s = idx - 4096; int b = s >> 3, q0 = (s & 7) * 8;
;       tok0 = NPROMPT + b * 64 + q0; nvis = 1088;
;       KI = (const u16*)(ws + OFF_KIS) + (size_t)b * 1088 * 64;
;       mrow0 = (u64*)(ws + OFF_MASKS) + (size_t)(b * 64 + q0) * 32; mld = 32;
;     }
;     ...
;     const u16* QI = (const u16*)(ws + OFF_QI);
;     const float* WI = (const float*)(ws + OFF_WI);
;     const int n16 = lane & 15, g4 = lane >> 4;
;     bf16x8 qa[4][2]; float4 wv[4];
; #pragma unroll
;     for (int pp = 0; pp < 4; pp++) {
;       const int ql = 2 * pp + (n16 >> 3), hh = n16 & 7;
; #pragma unroll
;       for (int kh = 0; kh < 2; kh++)
;         qa[pp][kh] = as_bf8(*(const uint4*)(QI + (size_t)(tok0 + ql) * 512 + hh * 64 + kh * 32 + 8 * g4));
;       wv[pp] = *(const float4*)(WI + (size_t)(tok0 + 2 * pp + (g4 >> 1)) * 8 + 4 * (g4 & 1));
;     }
.LBB0_554:
	s_or_b64 exec, exec, s[38:39]
	s_waitcnt vmcnt(0)
	s_waitcnt lgkmcnt(0)
	s_barrier
	s_load_dword s96, s[56:57], 0x0
	s_mov_b32 s97, 0
	s_waitcnt lgkmcnt(0)
	s_add_i32 s96, s96, s72
	s_cmpk_gt_i32 s96, 0x103f
	s_cbranch_scc1 .Lq_nopf
	s_and_b32 s36, s96, 0x100
	s_xor_b32 s37, s96, 0xff
	s_cmp_eq_u32 s36, 0
	s_cselect_b32 s38, s96, s37
	s_cmpk_gt_i32 s38, 0xfff
	s_cbranch_scc1 .Lq_sample
	s_lshl_b32 s37, s38, 1
	s_and_b32 s36, s38, 3
	s_and_b32 s37, s37, -8
	s_sub_i32 s37, 0x1ff8, s37
	s_lshl_b32 s36, s36, 13
	s_add_i32 s95, s37, s36
	s_branch .Lq_issue
.Lq_sample:
	s_add_i32 s36, s38, 0xfffff000
	s_lshr_b32 s36, s36, 3
	s_lshl_b32 s37, s38, 3
	s_and_b32 s37, s37, 56
	s_lshl_b32 s36, s36, 6
	s_or_b32 s36, s36, s37
	s_add_i32 s95, s36, 0x8000
.Lq_issue:
	v_add_u32_e32 v70, s95, v144
	v_add_u32_e32 v78, s95, v145
	v_ashrrev_i32_e32 v71, 31, v70
	v_ashrrev_i32_e32 v79, 31, v78
	v_lshlrev_b64 v[38:39], 10, v[70:71]
	v_lshlrev_b64 v[46:47], 5, v[78:79]
	v_add_u32_e32 v48, 2, v70
	v_add_u32_e32 v56, 2, v78
	v_add_u32_e32 v62, 4, v70
	v_add_u32_e32 v72, 4, v78
	v_add_u32_e32 v70, 6, v70
	v_add_u32_e32 v78, 6, v78
	v_ashrrev_i32_e32 v49, 31, v48
	v_ashrrev_i32_e32 v57, 31, v56
	v_ashrrev_i32_e32 v63, 31, v62
	v_ashrrev_i32_e32 v73, 31, v72
	v_ashrrev_i32_e32 v71, 31, v70
	v_ashrrev_i32_e32 v79, 31, v78
	v_lshlrev_b64 v[48:49], 10, v[48:49]
	v_lshlrev_b64 v[56:57], 5, v[56:57]
	v_lshlrev_b64 v[62:63], 10, v[62:63]
	v_lshlrev_b64 v[72:73], 5, v[72:73]
	v_lshlrev_b64 v[70:71], 10, v[70:71]
	v_lshlrev_b64 v[78:79], 5, v[78:79]
	v_lshl_add_u64 v[42:43], v[120:121], 0, v[38:39]
	v_lshl_add_u64 v[46:47], v[122:123], 0, v[46:47]
	v_lshl_add_u64 v[54:55], v[120:121], 0, v[48:49]
	v_lshl_add_u64 v[58:59], v[122:123], 0, v[56:57]
	v_lshl_add_u64 v[66:67], v[120:121], 0, v[62:63]
	v_lshl_add_u64 v[72:73], v[122:123], 0, v[72:73]
	v_lshl_add_u64 v[80:81], v[120:121], 0, v[70:71]
	v_lshl_add_u64 v[82:83], v[122:123], 0, v[78:79]
	global_load_dwordx4 v[38:41], v[42:43], off
	s_nop 0
	global_load_dwordx4 v[42:45], v[42:43], off offset:64
	s_nop 0
	global_load_dwordx4 v[46:49], v[46:47], off
	s_nop 0
	global_load_dwordx4 v[50:53], v[54:55], off
	s_nop 0
	global_load_dwordx4 v[54:57], v[54:55], off offset:64
	s_nop 0
	global_load_dwordx4 v[58:61], v[58:59], off
	s_nop 0
	global_load_dwordx4 v[62:65], v[66:67], off
	s_nop 0
	global_load_dwordx4 v[66:69], v[66:67], off offset:64
	s_nop 0
	global_load_dwordx4 v[70:73], v[72:73], off
	s_nop 0
	global_load_dwordx4 v[74:77], v[80:81], off
	s_nop 0
	global_load_dwordx4 v[78:81], v[80:81], off offset:64
	s_nop 0
	global_load_dwordx4 v[82:85], v[82:83], off
	s_mov_b32 s97, 1
.Lq_nopf:
	v_mul_u32_u24_e32 v30, s44, v133
	s_lshl_b64 s[36:37], s[58:59], s46
	s_add_u32 s36, s42, s36
	s_addc_u32 s37, s43, s37
	v_lshlrev_b32_e32 v30, 3, v30
	v_mov_b32_e32 v31, v119
	v_lshl_add_u64 v[30:31], s[36:37], 0, v[30:31]
	v_lshl_add_u64 v[32:33], v[136:137], 0, v[30:31]
	v_add_u32_e32 v6, v146, v149
	s_and_b32 s36, s74, 0x1ff
	s_cbranch_scc0 .Lsel_notail
	s_lshr_b32 s36, s36, 3
	s_lshl_b32 s37, s73, 10
	s_addk_i32 s37, 0xfc00
	v_cmp_le_u32_e32 vcc, s36, v154
	v_add_u32_e32 v7, s37, v6
	s_and_saveexec_b64 s[38:39], vcc
	ds_write_b128 v7, v[156:159]
	s_mov_b64 exec, s[38:39]

; __device__ void phase2(const Params& p, unsigned char* smem) {
;     ...
;           const u64 beq = __ballot(eq);
;           const uint32_t rank = __popcll(beq & ltmask);
;           const bool sel = gt || (eq && (eq_seen + rank) < need_eq);
;           const u64 m = __ballot(sel);
;           eq_seen += __popcll(beq);
;           if (lane == e) myword = m;
;         }
;         if (lane < 8) mrow[j * 8 + lane] = myword;
;         cur = nxt;
.Lsel_back7:
	v_writelane_b32 v16, s40, 7
	v_writelane_b32 v17, s41, 7
	s_mov_b64 exec, s[4:5]
	global_store_dwordx2 v[32:33], v[16:17], off
	s_mov_b64 exec, -1
	v_lshl_add_u64 v[32:33], v[32:33], 0, 64
	s_cmp_lt_u32 s66, s73
	s_cbranch_scc1 .Lsel_fl
	s_branch .LBB0_527

; #define PG8_STAGE(bufoff, gbase, voff) do { _Pragma("unroll") for (int _i = 0; _i < 2; ++_i) \
;         __builtin_amdgcn_global_load_lds((const unsigned*)((const char*)(gbase) + (voff)[_i]), (PG8_LAS unsigned*)(lds + (bufoff) + ldsw + _i * 8192), 16, 0, 0); } while (0)
; #define PG8_LDA(dst, b, h) do { _Pragma("unroll") for (int m = 0; m < 4; ++m) _Pragma("unroll") for (int k = 0; k < 2; ++k) dst[m][k] = *(const PG8_LAS bf16x8*)(lds + PG8_SA(b, h) + aoff + m * 2048 + k * 1024); } while (0)
; #define PG8_LDB(dst, b, h) do { _Pragma("unroll") for (int n = 0; n < 2; ++n) _Pragma("unroll") for (int k = 0; k < 2; ++k) dst[n][k] = *(const PG8_LAS bf16x8*)(lds + PG8_SB(b, h) + boff + n * 2048 + k * 1024); } while (0)
; #define PG8_MMA(ai, bj, At, Bt) do { __builtin_amdgcn_s_setprio(1); _Pragma("unroll") for (int m = 0; m < 4; ++m) _Pragma("unroll") for (int n = 0; n < 2; ++n) _Pragma("unroll") for (int k = 0; k < 2; ++k) \
;         acc[ai][bj][m][n] = __builtin_amdgcn_mfma_f32_16x16x32_bf16(Bt[n][k], At[m][k], acc[ai][bj][m][n], 0, 0, 0); __builtin_amdgcn_s_setprio(0); } while (0)
; #define PG8_WAIT_L(n) asm volatile("s_waitcnt lgkmcnt(" #n ")" ::: "memory")
; #define PG8_BAR __builtin_amdgcn_s_barrier()
; #define PG8_SCHED __builtin_amdgcn_sched_barrier(0)
; template <class Epi, class Sched>
; __device__ __forceinline__ void gemm_phase(PG8_LAS unsigned char* lds, const Gemm g, const Sched& S, const Epi& E) {
;     ...
;             PG8_LDB(B0, 0, 0); PG8_SCHED; PG8_LDA(At, 0, 0); PG8_STAGE(PG8_SA(1, 1), a1 + hstep, voffA);
;             PG8_WAIT_L(8); PG8_BAR; PG8_WAIT_L(0); PG8_MMA(0, 0, At, B0); PG8_BAR; PG8_SCHED;
;             PG8_LDB(B1, 0, 1); PG8_STAGE(PG8_SB(0, 0), b2, voffB);
;             PG8_BAR; PG8_WAIT_L(0); PG8_MMA(0, 1, At, B1); PG8_BAR;
;             PG8_LDA(At, 0, 1); PG8_STAGE(PG8_SA(0, 0), a2, voffA);
;             PG8_BAR; PG8_WAIT_L(0); PG8_MMA(1, 0, At, B0); PG8_BAR; PG8_SCHED;
.LBB0_800:
	ds_read_b128 v[138:141], v145
	ds_read_b128 v[162:165], v146
	ds_read_b128 v[166:169], v147
	ds_read_b128 v[170:173], v148
	s_add_u32 s28, s26, 0xfffc0080
	s_addc_u32 s29, s27, -1
	s_cmp_eq_u32 s58, 12
	s_cselect_b32 s31, s17, s29
	s_cselect_b32 s30, s54, s28
	s_cselect_b32 s29, s15, s57
	s_cselect_b32 s28, s55, s56
	s_mov_b32 m0, s51
	v_lshl_add_u64 v[206:207], s[26:27], 0, v[134:135]
	ds_read_b128 v[174:177], v143
	ds_read_b128 v[178:181], v143 offset:1024
	ds_read_b128 v[182:185], v143 offset:2048
	ds_read_b128 v[186:189], v143 offset:3072
	ds_read_b128 v[190:193], v143 offset:4096
	ds_read_b128 v[194:197], v143 offset:5120
	ds_read_b128 v[198:201], v143 offset:6144
	ds_read_b128 v[202:205], v143 offset:7168
	global_load_lds_dwordx4 v[206:207], off
	v_lshl_add_u64 v[206:207], s[26:27], 0, v[136:137]
	s_mov_b32 m0, s52
	s_nop 0
	global_load_lds_dwordx4 v[206:207], off
	s_waitcnt lgkmcnt(8)
	s_barrier
	s_waitcnt lgkmcnt(0)
	s_setprio 1
	s_waitcnt lgkmcnt(0)
	v_mfma_f32_16x16x32_bf16 v[126:129], v[138:141], v[174:177], v[126:129]
	v_mfma_f32_16x16x32_bf16 v[122:125], v[166:169], v[174:177], v[122:125]
	v_mfma_f32_16x16x32_bf16 v[110:113], v[138:141], v[182:185], v[110:113]
	v_mfma_f32_16x16x32_bf16 v[106:109], v[166:169], v[182:185], v[106:109]
	v_mfma_f32_16x16x32_bf16 v[94:97], v[138:141], v[190:193], v[94:97]
	v_mfma_f32_16x16x32_bf16 v[90:93], v[166:169], v[190:193], v[90:93]
	v_mfma_f32_16x16x32_bf16 v[78:81], v[138:141], v[198:201], v[78:81]
	v_mfma_f32_16x16x32_bf16 v[74:77], v[166:169], v[198:201], v[74:77]
	v_mfma_f32_16x16x32_bf16 v[126:129], v[162:165], v[178:181], v[126:129]
	v_mfma_f32_16x16x32_bf16 v[122:125], v[170:173], v[178:181], v[122:125]
	v_mfma_f32_16x16x32_bf16 v[110:113], v[162:165], v[186:189], v[110:113]
	v_mfma_f32_16x16x32_bf16 v[106:109], v[170:173], v[186:189], v[106:109]
	v_mfma_f32_16x16x32_bf16 v[94:97], v[162:165], v[194:197], v[94:97]
	v_mfma_f32_16x16x32_bf16 v[90:93], v[170:173], v[194:197], v[90:93]
	v_mfma_f32_16x16x32_bf16 v[78:81], v[162:165], v[202:205], v[78:81]
	v_mfma_f32_16x16x32_bf16 v[74:77], v[170:173], v[202:205], v[74:77]
	s_setprio 0
	s_barrier
	s_mov_b32 m0, s23
	v_lshl_add_u64 v[222:223], s[28:29], 0, v[130:131]
	ds_read_b128 v[206:209], v149
	ds_read_b128 v[210:213], v150
	ds_read_b128 v[214:217], v151
	ds_read_b128 v[218:221], v152
	global_load_lds_dwordx4 v[222:223], off
	v_lshl_add_u64 v[224:225], s[28:29], 0, v[132:133]
	s_mov_b32 m0, s25
	s_nop 0
	global_load_lds_dwordx4 v[224:225], off
	s_barrier
	s_waitcnt lgkmcnt(0)
	s_setprio 1
	s_waitcnt lgkmcnt(0)
	v_mfma_f32_16x16x32_bf16 v[118:121], v[206:209], v[174:177], v[118:121]
	v_mfma_f32_16x16x32_bf16 v[114:117], v[214:217], v[174:177], v[114:117]
	v_mfma_f32_16x16x32_bf16 v[102:105], v[206:209], v[182:185], v[102:105]
	v_mfma_f32_16x16x32_bf16 v[98:101], v[214:217], v[182:185], v[98:101]
	v_mfma_f32_16x16x32_bf16 v[86:89], v[206:209], v[190:193], v[86:89]
	v_mfma_f32_16x16x32_bf16 v[82:85], v[214:217], v[190:193], v[82:85]
	v_mfma_f32_16x16x32_bf16 v[70:73], v[206:209], v[198:201], v[70:73]
	v_mfma_f32_16x16x32_bf16 v[66:69], v[214:217], v[198:201], v[66:69]
	v_mfma_f32_16x16x32_bf16 v[118:121], v[210:213], v[178:181], v[118:121]
	v_mfma_f32_16x16x32_bf16 v[114:117], v[218:221], v[178:181], v[114:117]
	v_mfma_f32_16x16x32_bf16 v[102:105], v[210:213], v[186:189], v[102:105]
	v_mfma_f32_16x16x32_bf16 v[98:101], v[218:221], v[186:189], v[98:101]
	v_mfma_f32_16x16x32_bf16 v[86:89], v[210:213], v[194:197], v[86:89]
	v_mfma_f32_16x16x32_bf16 v[82:85], v[218:221], v[194:197], v[82:85]
	v_mfma_f32_16x16x32_bf16 v[70:73], v[210:213], v[202:205], v[70:73]
	v_mfma_f32_16x16x32_bf16 v[66:69], v[218:221], v[202:205], v[66:69]
	s_setprio 0
	s_mov_b32 m0, s38
	v_lshl_add_u64 v[226:227], s[30:31], 0, v[130:131]
	s_barrier
	ds_read_b128 v[174:177], v143 offset:16384
	ds_read_b128 v[178:181], v143 offset:17408
	ds_read_b128 v[182:185], v143 offset:18432
	ds_read_b128 v[186:189], v143 offset:19456
	ds_read_b128 v[190:193], v143 offset:20480
	ds_read_b128 v[194:197], v143 offset:21504
	ds_read_b128 v[198:201], v143 offset:22528
	ds_read_b128 v[202:205], v143 offset:23552
	global_load_lds_dwordx4 v[226:227], off
	v_lshl_add_u64 v[228:229], s[30:31], 0, v[132:133]
	s_mov_b32 m0, s39
	s_nop 0
	global_load_lds_dwordx4 v[228:229], off
	s_barrier
	s_waitcnt lgkmcnt(0)
	s_setprio 1
	s_waitcnt lgkmcnt(0)
	v_mfma_f32_16x16x32_bf16 v[62:65], v[138:141], v[174:177], v[62:65]
	v_mfma_f32_16x16x32_bf16 v[58:61], v[166:169], v[174:177], v[58:61]
	v_mfma_f32_16x16x32_bf16 v[46:49], v[138:141], v[182:185], v[46:49]
	v_mfma_f32_16x16x32_bf16 v[42:45], v[166:169], v[182:185], v[42:45]
	v_mfma_f32_16x16x32_bf16 v[30:33], v[138:141], v[190:193], v[30:33]
	v_mfma_f32_16x16x32_bf16 v[26:29], v[166:169], v[190:193], v[26:29]
	v_mfma_f32_16x16x32_bf16 v[14:17], v[138:141], v[198:201], v[14:17]
	v_mfma_f32_16x16x32_bf16 v[10:13], v[166:169], v[198:201], v[10:13]
	v_mfma_f32_16x16x32_bf16 v[62:65], v[162:165], v[178:181], v[62:65]
	v_mfma_f32_16x16x32_bf16 v[58:61], v[170:173], v[178:181], v[58:61]
	v_mfma_f32_16x16x32_bf16 v[46:49], v[162:165], v[186:189], v[46:49]
	v_mfma_f32_16x16x32_bf16 v[42:45], v[170:173], v[186:189], v[42:45]
	v_mfma_f32_16x16x32_bf16 v[30:33], v[162:165], v[194:197], v[30:33]
	v_mfma_f32_16x16x32_bf16 v[26:29], v[170:173], v[194:197], v[26:29]
	v_mfma_f32_16x16x32_bf16 v[14:17], v[162:165], v[202:205], v[14:17]
	v_mfma_f32_16x16x32_bf16 v[10:13], v[170:173], v[202:205], v[10:13]
	s_setprio 0
	s_barrier
; #define PG8_STAGE(bufoff, gbase, voff) do { _Pragma("unroll") for (int _i = 0; _i < 2; ++_i) \
;         __builtin_amdgcn_global_load_lds((const unsigned*)((const char*)(gbase) + (voff)[_i]), (PG8_LAS unsigned*)(lds + (bufoff) + ldsw + _i * 8192), 16, 0, 0); } while (0)
; #define PG8_LDA(dst, b, h) do { _Pragma("unroll") for (int m = 0; m < 4; ++m) _Pragma("unroll") for (int k = 0; k < 2; ++k) dst[m][k] = *(const PG8_LAS bf16x8*)(lds + PG8_SA(b, h) + aoff + m * 2048 + k * 1024); } while (0)
; #define PG8_LDB(dst, b, h) do { _Pragma("unroll") for (int n = 0; n < 2; ++n) _Pragma("unroll") for (int k = 0; k < 2; ++k) dst[n][k] = *(const PG8_LAS bf16x8*)(lds + PG8_SB(b, h) + boff + n * 2048 + k * 1024); } while (0)
; #define PG8_MMA(ai, bj, At, Bt) do { __builtin_amdgcn_s_setprio(1); _Pragma("unroll") for (int m = 0; m < 4; ++m) _Pragma("unroll") for (int n = 0; n < 2; ++n) _Pragma("unroll") for (int k = 0; k < 2; ++k) \
;         acc[ai][bj][m][n] = __builtin_amdgcn_mfma_f32_16x16x32_bf16(Bt[n][k], At[m][k], acc[ai][bj][m][n], 0, 0, 0); __builtin_amdgcn_s_setprio(0); } while (0)
; #define PG8_WAIT_V(n) asm volatile("s_waitcnt vmcnt(" #n ")" ::: "memory")
; #define PG8_WAIT_L(n) asm volatile("s_waitcnt lgkmcnt(" #n ")" ::: "memory")
; #define PG8_BAR __builtin_amdgcn_s_barrier()
; #define PG8_SCHED __builtin_amdgcn_sched_barrier(0)
; template <class Epi, class Sched>
; __device__ __forceinline__ void gemm_phase(PG8_LAS unsigned char* lds, const Gemm g, const Sched& S, const Epi& E) {
;     ...
;             PG8_STAGE(PG8_SB(0, 1), b2 + hstep, voffB);
;             PG8_WAIT_V(6); PG8_BAR; PG8_MMA(1, 1, At, B1); PG8_BAR;
;             PG8_LDB(B0, 1, 0); PG8_SCHED; PG8_LDA(At, 1, 0); PG8_STAGE(PG8_SA(0, 1), a2 + hstep, voffA);
;             PG8_WAIT_L(8); PG8_BAR; PG8_WAIT_L(0); PG8_MMA(0, 0, At, B0); PG8_BAR; PG8_SCHED;
;             PG8_LDB(B1, 1, 1); PG8_STAGE(PG8_SB(1, 0), b3, voffB);
;             PG8_BAR; PG8_WAIT_L(0); PG8_MMA(0, 1, At, B1); PG8_BAR;
;             PG8_LDA(At, 1, 1); PG8_STAGE(PG8_SA(1, 0), a3, voffA);
	s_add_u32 s60, s28, 0x40000
	s_addc_u32 s61, s29, 0
	s_mov_b32 m0, s40
	v_lshl_add_u64 v[138:139], s[60:61], 0, v[130:131]
	global_load_lds_dwordx4 v[138:139], off
	v_lshl_add_u64 v[138:139], s[60:61], 0, v[132:133]
	s_mov_b32 m0, s41
	s_nop 0
	global_load_lds_dwordx4 v[138:139], off
	s_waitcnt vmcnt(6)
	s_barrier
	s_setprio 1
	v_mfma_f32_16x16x32_bf16 v[54:57], v[206:209], v[174:177], v[54:57]
	v_mfma_f32_16x16x32_bf16 v[50:53], v[214:217], v[174:177], v[50:53]
	v_mfma_f32_16x16x32_bf16 v[38:41], v[206:209], v[182:185], v[38:41]
	v_mfma_f32_16x16x32_bf16 v[34:37], v[214:217], v[182:185], v[34:37]
	v_mfma_f32_16x16x32_bf16 v[22:25], v[206:209], v[190:193], v[22:25]
	v_mfma_f32_16x16x32_bf16 v[18:21], v[214:217], v[190:193], v[18:21]
	v_mfma_f32_16x16x32_bf16 v[6:9], v[206:209], v[198:201], v[6:9]
	v_mfma_f32_16x16x32_bf16 v[2:5], v[214:217], v[198:201], v[2:5]
	v_mfma_f32_16x16x32_bf16 v[54:57], v[210:213], v[178:181], v[54:57]
	v_mfma_f32_16x16x32_bf16 v[50:53], v[218:221], v[178:181], v[50:53]
	v_mfma_f32_16x16x32_bf16 v[38:41], v[210:213], v[186:189], v[38:41]
	v_mfma_f32_16x16x32_bf16 v[34:37], v[218:221], v[186:189], v[34:37]
	v_mfma_f32_16x16x32_bf16 v[22:25], v[210:213], v[194:197], v[22:25]
	v_mfma_f32_16x16x32_bf16 v[18:21], v[218:221], v[194:197], v[18:21]
	v_mfma_f32_16x16x32_bf16 v[6:9], v[210:213], v[202:205], v[6:9]
	v_mfma_f32_16x16x32_bf16 v[2:5], v[218:221], v[202:205], v[2:5]
	s_setprio 0
	s_barrier
	ds_read_b128 v[138:141], v153
	ds_read_b128 v[162:165], v154
	ds_read_b128 v[166:169], v155
	ds_read_b128 v[170:173], v156
	s_add_u32 s30, s30, 0x40000
	s_addc_u32 s31, s31, 0
	s_mov_b32 m0, s42
	v_lshl_add_u64 v[206:207], s[30:31], 0, v[130:131]
	ds_read_b128 v[174:177], v143 offset:32768
	ds_read_b128 v[178:181], v143 offset:33792
	ds_read_b128 v[182:185], v143 offset:34816
	ds_read_b128 v[186:189], v143 offset:35840
	ds_read_b128 v[190:193], v143 offset:36864
	ds_read_b128 v[194:197], v143 offset:37888
	ds_read_b128 v[198:201], v143 offset:38912
	ds_read_b128 v[202:205], v143 offset:39936
	global_load_lds_dwordx4 v[206:207], off
	v_lshl_add_u64 v[206:207], s[30:31], 0, v[132:133]
	s_mov_b32 m0, s43
	s_nop 0
	global_load_lds_dwordx4 v[206:207], off
	s_waitcnt lgkmcnt(8)
	s_barrier
	s_waitcnt lgkmcnt(0)
	s_setprio 1
	s_waitcnt lgkmcnt(0)
	v_mfma_f32_16x16x32_bf16 v[126:129], v[138:141], v[174:177], v[126:129]
	v_mfma_f32_16x16x32_bf16 v[122:125], v[166:169], v[174:177], v[122:125]
	v_mfma_f32_16x16x32_bf16 v[110:113], v[138:141], v[182:185], v[110:113]
	v_mfma_f32_16x16x32_bf16 v[106:109], v[166:169], v[182:185], v[106:109]
	v_mfma_f32_16x16x32_bf16 v[94:97], v[138:141], v[190:193], v[94:97]
	v_mfma_f32_16x16x32_bf16 v[90:93], v[166:169], v[190:193], v[90:93]
	v_mfma_f32_16x16x32_bf16 v[78:81], v[138:141], v[198:201], v[78:81]
	v_mfma_f32_16x16x32_bf16 v[74:77], v[166:169], v[198:201], v[74:77]
	v_mfma_f32_16x16x32_bf16 v[126:129], v[162:165], v[178:181], v[126:129]
	v_mfma_f32_16x16x32_bf16 v[122:125], v[170:173], v[178:181], v[122:125]
	v_mfma_f32_16x16x32_bf16 v[110:113], v[162:165], v[186:189], v[110:113]
	v_mfma_f32_16x16x32_bf16 v[106:109], v[170:173], v[186:189], v[106:109]
	v_mfma_f32_16x16x32_bf16 v[94:97], v[162:165], v[194:197], v[94:97]
	v_mfma_f32_16x16x32_bf16 v[90:93], v[170:173], v[194:197], v[90:93]
	v_mfma_f32_16x16x32_bf16 v[78:81], v[162:165], v[202:205], v[78:81]
	v_mfma_f32_16x16x32_bf16 v[74:77], v[170:173], v[202:205], v[74:77]
	s_setprio 0
	s_barrier
	s_mov_b32 m0, s44
	v_lshl_add_u64 v[222:223], v[222:223], 0, s[8:9]
	ds_read_b128 v[206:209], v157
	ds_read_b128 v[210:213], v158
	ds_read_b128 v[214:217], v159
	ds_read_b128 v[218:221], v160
	global_load_lds_dwordx4 v[222:223], off
	v_lshl_add_u64 v[222:223], v[224:225], 0, s[8:9]
	s_mov_b32 m0, s45
	s_nop 0
	global_load_lds_dwordx4 v[222:223], off
	s_barrier
	s_waitcnt lgkmcnt(0)
	s_setprio 1
	s_waitcnt lgkmcnt(0)
	v_mfma_f32_16x16x32_bf16 v[118:121], v[206:209], v[174:177], v[118:121]
	v_mfma_f32_16x16x32_bf16 v[114:117], v[214:217], v[174:177], v[114:117]
	v_mfma_f32_16x16x32_bf16 v[102:105], v[206:209], v[182:185], v[102:105]
	v_mfma_f32_16x16x32_bf16 v[98:101], v[214:217], v[182:185], v[98:101]
	v_mfma_f32_16x16x32_bf16 v[86:89], v[206:209], v[190:193], v[86:89]
	v_mfma_f32_16x16x32_bf16 v[82:85], v[214:217], v[190:193], v[82:85]
	v_mfma_f32_16x16x32_bf16 v[70:73], v[206:209], v[198:201], v[70:73]
	v_mfma_f32_16x16x32_bf16 v[66:69], v[214:217], v[198:201], v[66:69]
	v_mfma_f32_16x16x32_bf16 v[118:121], v[210:213], v[178:181], v[118:121]
	v_mfma_f32_16x16x32_bf16 v[114:117], v[218:221], v[178:181], v[114:117]
	v_mfma_f32_16x16x32_bf16 v[102:105], v[210:213], v[186:189], v[102:105]
	v_mfma_f32_16x16x32_bf16 v[98:101], v[218:221], v[186:189], v[98:101]
	v_mfma_f32_16x16x32_bf16 v[86:89], v[210:213], v[194:197], v[86:89]
	v_mfma_f32_16x16x32_bf16 v[82:85], v[218:221], v[194:197], v[82:85]
	v_mfma_f32_16x16x32_bf16 v[70:73], v[210:213], v[202:205], v[70:73]
	v_mfma_f32_16x16x32_bf16 v[66:69], v[218:221], v[202:205], v[66:69]
	s_setprio 0
	s_mov_b32 m0, s46
	v_lshl_add_u64 v[222:223], v[226:227], 0, s[8:9]
	s_barrier
	ds_read_b128 v[174:177], v143 offset:49152
	ds_read_b128 v[178:181], v143 offset:50176
	ds_read_b128 v[182:185], v143 offset:51200
	ds_read_b128 v[186:189], v143 offset:52224
	ds_read_b128 v[190:193], v143 offset:53248
	ds_read_b128 v[194:197], v143 offset:54272
	ds_read_b128 v[198:201], v143 offset:55296
	ds_read_b128 v[202:205], v143 offset:56320
	global_load_lds_dwordx4 v[222:223], off
	v_lshl_add_u64 v[222:223], v[228:229], 0, s[8:9]
	s_mov_b32 m0, s47
	s_nop 0
	global_load_lds_dwordx4 v[222:223], off
	s_barrier
; #define PG8_STAGE(bufoff, gbase, voff) do { _Pragma("unroll") for (int _i = 0; _i < 2; ++_i) \
;         __builtin_amdgcn_global_load_lds((const unsigned*)((const char*)(gbase) + (voff)[_i]), (PG8_LAS unsigned*)(lds + (bufoff) + ldsw + _i * 8192), 16, 0, 0); } while (0)
; #define PG8_MMA(ai, bj, At, Bt) do { __builtin_amdgcn_s_setprio(1); _Pragma("unroll") for (int m = 0; m < 4; ++m) _Pragma("unroll") for (int n = 0; n < 2; ++n) _Pragma("unroll") for (int k = 0; k < 2; ++k) \
;         acc[ai][bj][m][n] = __builtin_amdgcn_mfma_f32_16x16x32_bf16(Bt[n][k], At[m][k], acc[ai][bj][m][n], 0, 0, 0); __builtin_amdgcn_s_setprio(0); } while (0)
; #define PG8_WAIT_V(n) asm volatile("s_waitcnt vmcnt(" #n ")" ::: "memory")
; #define PG8_WAIT_L(n) asm volatile("s_waitcnt lgkmcnt(" #n ")" ::: "memory")
; #define PG8_BAR __builtin_amdgcn_s_barrier()
; #define PG8_SCHED __builtin_amdgcn_sched_barrier(0)
; template <class Epi, class Sched>
; __device__ __forceinline__ void gemm_phase(PG8_LAS unsigned char* lds, const Gemm g, const Sched& S, const Epi& E) {
;     ...
;             PG8_BAR; PG8_WAIT_L(0); PG8_MMA(1, 0, At, B0); PG8_BAR; PG8_SCHED;
;             PG8_STAGE(PG8_SB(1, 1), b3 + hstep, voffB);
;             PG8_WAIT_V(6); PG8_BAR; PG8_MMA(1, 1, At, B1); PG8_BAR;
;   __device__ __forceinline__ void operator()(const acc8_t& acc, const pg8::Unit& u, int wr, int wc, int fr, int fq) const {
;     u16* H = (u16*)(ws + OFF_H);
;     const float* rss = (const float*)(ws + OFF_ROWSS);
; #pragma unroll
;     for (int ai = 0; ai < 2; ai++)
; #pragma unroll
;       for (int m = 0; m < 4; m++) {
;         const size_t token = EPI_TOKEN(u, ai, m);
;         const float rs = rsqrtf(rss[token] * (1.f / 1024.f) + 1e-6f);
; #pragma unroll
;         for (int bj = 0; bj < 2; bj++)
; #pragma unroll
;           for (int n = 0; n < 2; n++) {
;             const int f = EPI_COL(u, bj, n);
;             const float v0 = fmaxf(acc[ai][bj][m][n][0] * rs, 0.f), v1 = fmaxf(acc[ai][bj][m][n][1] * rs, 0.f);
;             const float v2 = fmaxf(acc[ai][bj][m][n][2] * rs, 0.f), v3 = fmaxf(acc[ai][bj][m][n][3] * rs, 0.f);
;             uint2 o; o.x = pack2(v0 * v0, v1 * v1); o.y = pack2(v2 * v2, v3 * v3);
;             *(uint2*)(H + token * 4096 + f) = o;
;           }
;       }
;   }
	s_waitcnt lgkmcnt(0)
	s_setprio 1
	s_waitcnt lgkmcnt(0)
	v_mfma_f32_16x16x32_bf16 v[62:65], v[138:141], v[174:177], v[62:65]
	v_mfma_f32_16x16x32_bf16 v[58:61], v[166:169], v[174:177], v[58:61]
	v_mfma_f32_16x16x32_bf16 v[46:49], v[138:141], v[182:185], v[46:49]
	v_mfma_f32_16x16x32_bf16 v[42:45], v[166:169], v[182:185], v[42:45]
	v_mfma_f32_16x16x32_bf16 v[30:33], v[138:141], v[190:193], v[30:33]
	v_mfma_f32_16x16x32_bf16 v[26:29], v[166:169], v[190:193], v[26:29]
	v_mfma_f32_16x16x32_bf16 v[14:17], v[138:141], v[198:201], v[14:17]
	v_mfma_f32_16x16x32_bf16 v[10:13], v[166:169], v[198:201], v[10:13]
	v_mfma_f32_16x16x32_bf16 v[62:65], v[162:165], v[178:181], v[62:65]
	v_mfma_f32_16x16x32_bf16 v[58:61], v[170:173], v[178:181], v[58:61]
	v_mfma_f32_16x16x32_bf16 v[46:49], v[162:165], v[186:189], v[46:49]
	v_mfma_f32_16x16x32_bf16 v[42:45], v[170:173], v[186:189], v[42:45]
	v_mfma_f32_16x16x32_bf16 v[30:33], v[162:165], v[194:197], v[30:33]
	v_mfma_f32_16x16x32_bf16 v[26:29], v[170:173], v[194:197], v[26:29]
	v_mfma_f32_16x16x32_bf16 v[14:17], v[162:165], v[202:205], v[14:17]
	v_mfma_f32_16x16x32_bf16 v[10:13], v[170:173], v[202:205], v[10:13]
	s_setprio 0
	s_barrier
	s_add_u32 s28, s28, 0x40080
	s_addc_u32 s29, s29, 0
	s_mov_b32 m0, s48
	v_lshl_add_u64 v[138:139], s[28:29], 0, v[130:131]
	global_load_lds_dwordx4 v[138:139], off
	v_lshl_add_u64 v[138:139], s[28:29], 0, v[132:133]
	s_mov_b32 m0, s49
	s_nop 0
	global_load_lds_dwordx4 v[138:139], off
	s_waitcnt vmcnt(6)
	s_barrier
	s_setprio 1
	v_mfma_f32_16x16x32_bf16 v[54:57], v[206:209], v[174:177], v[54:57]
	v_mfma_f32_16x16x32_bf16 v[50:53], v[214:217], v[174:177], v[50:53]
	v_mfma_f32_16x16x32_bf16 v[38:41], v[206:209], v[182:185], v[38:41]
	v_mfma_f32_16x16x32_bf16 v[34:37], v[214:217], v[182:185], v[34:37]
	v_mfma_f32_16x16x32_bf16 v[22:25], v[206:209], v[190:193], v[22:25]
	v_mfma_f32_16x16x32_bf16 v[18:21], v[214:217], v[190:193], v[18:21]
	v_mfma_f32_16x16x32_bf16 v[6:9], v[206:209], v[198:201], v[6:9]
	v_mfma_f32_16x16x32_bf16 v[2:5], v[214:217], v[198:201], v[2:5]
	v_mfma_f32_16x16x32_bf16 v[54:57], v[210:213], v[178:181], v[54:57]
	v_mfma_f32_16x16x32_bf16 v[50:53], v[218:221], v[178:181], v[50:53]
	v_mfma_f32_16x16x32_bf16 v[38:41], v[210:213], v[186:189], v[38:41]
	v_mfma_f32_16x16x32_bf16 v[34:37], v[218:221], v[186:189], v[34:37]
	v_mfma_f32_16x16x32_bf16 v[22:25], v[210:213], v[194:197], v[22:25]
	v_mfma_f32_16x16x32_bf16 v[18:21], v[218:221], v[194:197], v[18:21]
	v_mfma_f32_16x16x32_bf16 v[6:9], v[210:213], v[202:205], v[6:9]
	v_mfma_f32_16x16x32_bf16 v[2:5], v[218:221], v[202:205], v[2:5]
	s_setprio 0
	s_add_i32 s58, s58, 2
	s_add_u32 s26, s26, 0x100
	s_addc_u32 s27, s27, 0
	s_add_u32 s56, s56, 0x100
	s_addc_u32 s57, s57, 0
	s_cmp_gt_u32 s58, 13
	s_barrier
	s_cbranch_scc0 .LBB0_800
	v_lshl_add_u32 v140, s24, 8, v142
	v_ashrrev_i32_e32 v141, 31, v140
	v_lshl_add_u64 v[138:139], v[140:141], 2, s[12:13]
	global_load_dword v166, v[138:139], off
	global_load_dword v176, v[138:139], off offset:64
	global_load_dword v177, v[138:139], off offset:128
	global_load_dword v178, v[138:139], off offset:192
	global_load_dword v179, v[138:139], off offset:512
	global_load_dword v180, v[138:139], off offset:576
	global_load_dword v181, v[138:139], off offset:640
	global_load_dword v182, v[138:139], off offset:704
	v_lshlrev_b64 v[164:165], 13, v[140:141]
	v_lshl_or_b32 v138, s22, 8, v144
	v_ashrrev_i32_e32 v139, 31, v138
	v_or_b32_e32 v162, 16, v140
	v_lshlrev_b64 v[138:139], 1, v[138:139]
	v_lshl_add_u64 v[164:165], s[10:11], 0, v[164:165]
	v_ashrrev_i32_e32 v163, 31, v162
	v_lshl_add_u64 v[164:165], v[164:165], 0, v[138:139]
	s_mov_b32 s22, s14
	s_mov_b32 s24, s16
	s_mov_b64 s[28:29], s[20:21]
	s_mov_b64 s[26:27], s[18:19]
	s_waitcnt vmcnt(0)
	v_fmamk_f32 v141, v166, 0x3a800000, v161
	v_mul_f32_e32 v166, 0x4b800000, v141
	v_cmp_gt_f32_e32 vcc, s53, v141
	s_nop 1
	v_cndmask_b32_e32 v141, v141, v166, vcc
	v_rsq_f32_e32 v141, v141
	v_lshl_add_u64 v[166:167], v[162:163], 2, s[12:13]
	v_mul_f32_e32 v168, 0x45800000, v141
	v_cndmask_b32_e32 v141, v141, v168, vcc
	v_mul_f32_e32 v126, v126, v141
	v_mul_f32_e32 v127, v127, v141
	v_mul_f32_e32 v128, v128, v141
	v_mul_f32_e32 v129, v129, v141
	v_mul_f32_e32 v122, v122, v141
	v_mul_f32_e32 v123, v123, v141
	v_mul_f32_e32 v124, v124, v141
	v_mul_f32_e32 v125, v125, v141
	v_mul_f32_e32 v168, v118, v141
	v_mul_f32_e32 v169, v119, v141
	v_mul_f32_e32 v170, v120, v141
	v_mul_f32_e32 v171, v121, v141
	v_mul_f32_e32 v172, v114, v141
	v_mul_f32_e32 v173, v115, v141
	v_mul_f32_e32 v174, v116, v141
	v_mul_f32_e32 v141, v117, v141
	v_max_f32_e32 v114, 0, v126
	v_max_f32_e32 v115, 0, v127
	v_max_f32_e32 v116, 0, v128
	v_max_f32_e32 v117, 0, v129
	v_max_f32_e32 v118, 0, v122
	v_max_f32_e32 v119, 0, v123
	v_max_f32_e32 v120, 0, v124
	v_max_f32_e32 v121, 0, v125
	v_max_f32_e32 v122, 0, v168
	v_max_f32_e32 v123, 0, v169
	v_max_f32_e32 v124, 0, v170
	v_max_f32_e32 v125, 0, v171
	v_max_f32_e32 v126, 0, v172
	v_max_f32_e32 v127, 0, v173
	v_max_f32_e32 v128, 0, v174
	v_max_f32_e32 v129, 0, v141
	v_pk_mul_f32 v[114:115], v[114:115], v[114:115]
	v_pk_mul_f32 v[116:117], v[116:117], v[116:117]
	v_pk_mul_f32 v[118:119], v[118:119], v[118:119]
	v_pk_mul_f32 v[120:121], v[120:121], v[120:121]
	v_pk_mul_f32 v[122:123], v[122:123], v[122:123]
	v_pk_mul_f32 v[124:125], v[124:125], v[124:125]
	v_pk_mul_f32 v[126:127], v[126:127], v[126:127]
	v_pk_mul_f32 v[128:129], v[128:129], v[128:129]
	v_cvt_pk_bf16_f32 v114, v114, v115
	v_cvt_pk_bf16_f32 v115, v116, v117
	v_cvt_pk_bf16_f32 v116, v118, v119
	v_cvt_pk_bf16_f32 v117, v120, v121
	v_cvt_pk_bf16_f32 v118, v122, v123
;   __device__ __forceinline__ void operator()(const acc8_t& acc, const pg8::Unit& u, int wr, int wc, int fr, int fq) const {
;     ...
; #pragma unroll
;     for (int ai = 0; ai < 2; ai++)
; #pragma unroll
;       for (int m = 0; m < 4; m++) {
;         const size_t token = EPI_TOKEN(u, ai, m);
;         const float rs = rsqrtf(rss[token] * (1.f / 1024.f) + 1e-6f);
; #pragma unroll
;         for (int bj = 0; bj < 2; bj++)
; #pragma unroll
;           for (int n = 0; n < 2; n++) {
;             const int f = EPI_COL(u, bj, n);
;             const float v0 = fmaxf(acc[ai][bj][m][n][0] * rs, 0.f), v1 = fmaxf(acc[ai][bj][m][n][1] * rs, 0.f);
;             const float v2 = fmaxf(acc[ai][bj][m][n][2] * rs, 0.f), v3 = fmaxf(acc[ai][bj][m][n][3] * rs, 0.f);
;             uint2 o; o.x = pack2(v0 * v0, v1 * v1); o.y = pack2(v2 * v2, v3 * v3);
;             *(uint2*)(H + token * 4096 + f) = o;
;           }
	v_cvt_pk_bf16_f32 v119, v124, v125
	v_cvt_pk_bf16_f32 v120, v126, v127
	v_cvt_pk_bf16_f32 v121, v128, v129
	global_store_dwordx2 v[164:165], v[114:115], off
	global_store_dwordx2 v[164:165], v[116:117], off offset:32
	global_store_dwordx2 v[164:165], v[118:119], off offset:256
	global_store_dwordx2 v[164:165], v[120:121], off offset:288
	v_mov_b32_e32 v118, v176
	v_lshlrev_b64 v[116:117], 13, v[162:163]
	v_or_b32_e32 v114, 32, v140
	v_lshl_add_u64 v[116:117], s[10:11], 0, v[116:117]
	v_ashrrev_i32_e32 v115, 31, v114
	v_lshl_add_u64 v[116:117], v[116:117], 0, v[138:139]
	v_fmamk_f32 v118, v118, 0x3a800000, v161
	v_mul_f32_e32 v119, 0x4b800000, v118
	v_cmp_gt_f32_e32 vcc, s53, v118
	s_nop 1
	v_cndmask_b32_e32 v118, v118, v119, vcc
	v_rsq_f32_e32 v120, v118
	v_lshl_add_u64 v[118:119], v[114:115], 2, s[12:13]
	v_mul_f32_e32 v121, 0x45800000, v120
	v_cndmask_b32_e32 v120, v120, v121, vcc
	v_mul_f32_e32 v110, v110, v120
	v_mul_f32_e32 v111, v111, v120
	v_mul_f32_e32 v112, v112, v120
	v_mul_f32_e32 v113, v113, v120
	v_mul_f32_e32 v106, v106, v120
	v_mul_f32_e32 v107, v107, v120
	v_mul_f32_e32 v108, v108, v120
	v_mul_f32_e32 v109, v109, v120
	v_mul_f32_e32 v121, v102, v120
	v_mul_f32_e32 v122, v103, v120
	v_mul_f32_e32 v123, v104, v120
	v_mul_f32_e32 v124, v105, v120
	v_mul_f32_e32 v125, v98, v120
	v_mul_f32_e32 v126, v99, v120
	v_mul_f32_e32 v127, v100, v120
	v_mul_f32_e32 v120, v101, v120
	v_max_f32_e32 v98, 0, v110
	v_max_f32_e32 v99, 0, v111
	v_max_f32_e32 v100, 0, v112
	v_max_f32_e32 v101, 0, v113
	v_max_f32_e32 v102, 0, v106
	v_max_f32_e32 v103, 0, v107
	v_max_f32_e32 v104, 0, v108
	v_max_f32_e32 v105, 0, v109
	v_max_f32_e32 v106, 0, v121
	v_max_f32_e32 v107, 0, v122
	v_max_f32_e32 v108, 0, v123
	v_max_f32_e32 v109, 0, v124
	v_max_f32_e32 v110, 0, v125
	v_max_f32_e32 v111, 0, v126
	v_max_f32_e32 v112, 0, v127
	v_max_f32_e32 v113, 0, v120
	v_pk_mul_f32 v[98:99], v[98:99], v[98:99]
	v_pk_mul_f32 v[100:101], v[100:101], v[100:101]
	v_pk_mul_f32 v[102:103], v[102:103], v[102:103]
	v_pk_mul_f32 v[104:105], v[104:105], v[104:105]
	v_pk_mul_f32 v[106:107], v[106:107], v[106:107]
	v_pk_mul_f32 v[108:109], v[108:109], v[108:109]
	v_pk_mul_f32 v[110:111], v[110:111], v[110:111]
	v_pk_mul_f32 v[112:113], v[112:113], v[112:113]
	v_cvt_pk_bf16_f32 v98, v98, v99
	v_cvt_pk_bf16_f32 v99, v100, v101
	v_cvt_pk_bf16_f32 v100, v102, v103
	v_cvt_pk_bf16_f32 v101, v104, v105
	v_cvt_pk_bf16_f32 v102, v106, v107
	v_cvt_pk_bf16_f32 v103, v108, v109
	v_cvt_pk_bf16_f32 v104, v110, v111
	v_cvt_pk_bf16_f32 v105, v112, v113
	global_store_dwordx2 v[116:117], v[98:99], off
	global_store_dwordx2 v[116:117], v[100:101], off offset:32
	global_store_dwordx2 v[116:117], v[102:103], off offset:256
	global_store_dwordx2 v[116:117], v[104:105], off offset:288
	v_mov_b32_e32 v102, v177
	v_lshlrev_b64 v[100:101], 13, v[114:115]
	v_or_b32_e32 v98, 48, v140
	v_lshl_add_u64 v[100:101], s[10:11], 0, v[100:101]
	v_ashrrev_i32_e32 v99, 31, v98
	v_lshl_add_u64 v[100:101], v[100:101], 0, v[138:139]
	v_fmamk_f32 v102, v102, 0x3a800000, v161
	v_mul_f32_e32 v103, 0x4b800000, v102
	v_cmp_gt_f32_e32 vcc, s53, v102
	s_nop 1
	v_cndmask_b32_e32 v102, v102, v103, vcc
	v_rsq_f32_e32 v104, v102
	v_lshl_add_u64 v[102:103], v[98:99], 2, s[12:13]
	v_mul_f32_e32 v105, 0x45800000, v104
	v_cndmask_b32_e32 v104, v104, v105, vcc
	v_mul_f32_e32 v94, v94, v104
	v_mul_f32_e32 v95, v95, v104
	v_mul_f32_e32 v96, v96, v104
	v_mul_f32_e32 v97, v97, v104
	v_mul_f32_e32 v90, v90, v104
	v_mul_f32_e32 v91, v91, v104
	v_mul_f32_e32 v92, v92, v104
	v_mul_f32_e32 v93, v93, v104
	v_mul_f32_e32 v105, v86, v104
	v_mul_f32_e32 v106, v87, v104
	v_mul_f32_e32 v107, v88, v104
	v_mul_f32_e32 v108, v89, v104
	v_mul_f32_e32 v109, v82, v104
	v_mul_f32_e32 v110, v83, v104
	v_mul_f32_e32 v111, v84, v104
	v_mul_f32_e32 v104, v85, v104
	v_max_f32_e32 v82, 0, v94
	v_max_f32_e32 v83, 0, v95
	v_max_f32_e32 v84, 0, v96
	v_max_f32_e32 v85, 0, v97
	v_max_f32_e32 v86, 0, v90
	v_max_f32_e32 v87, 0, v91
	v_max_f32_e32 v88, 0, v92
	v_max_f32_e32 v89, 0, v93
	v_max_f32_e32 v90, 0, v105
	v_max_f32_e32 v91, 0, v106
	v_max_f32_e32 v92, 0, v107
	v_max_f32_e32 v93, 0, v108
	v_max_f32_e32 v94, 0, v109
	v_max_f32_e32 v95, 0, v110
	v_max_f32_e32 v96, 0, v111
	v_max_f32_e32 v97, 0, v104
	v_pk_mul_f32 v[82:83], v[82:83], v[82:83]
	v_pk_mul_f32 v[84:85], v[84:85], v[84:85]
	v_pk_mul_f32 v[86:87], v[86:87], v[86:87]
	v_pk_mul_f32 v[88:89], v[88:89], v[88:89]
	v_pk_mul_f32 v[90:91], v[90:91], v[90:91]
	v_pk_mul_f32 v[92:93], v[92:93], v[92:93]
	v_pk_mul_f32 v[94:95], v[94:95], v[94:95]
	v_pk_mul_f32 v[96:97], v[96:97], v[96:97]
	v_cvt_pk_bf16_f32 v82, v82, v83
	v_cvt_pk_bf16_f32 v83, v84, v85
	v_cvt_pk_bf16_f32 v84, v86, v87
	v_cvt_pk_bf16_f32 v85, v88, v89
	v_cvt_pk_bf16_f32 v86, v90, v91
	v_cvt_pk_bf16_f32 v87, v92, v93
	v_cvt_pk_bf16_f32 v88, v94, v95
	v_cvt_pk_bf16_f32 v89, v96, v97
	global_store_dwordx2 v[100:101], v[82:83], off
	global_store_dwordx2 v[100:101], v[84:85], off offset:32
	global_store_dwordx2 v[100:101], v[86:87], off offset:256
	global_store_dwordx2 v[100:101], v[88:89], off offset:288
	v_mov_b32_e32 v86, v178
	v_lshlrev_b64 v[84:85], 13, v[98:99]
	v_add_u32_e32 v82, 0x80, v140
	v_lshl_add_u64 v[84:85], s[10:11], 0, v[84:85]
	v_ashrrev_i32_e32 v83, 31, v82
	v_lshl_add_u64 v[84:85], v[84:85], 0, v[138:139]
	v_fmamk_f32 v86, v86, 0x3a800000, v161
	v_mul_f32_e32 v87, 0x4b800000, v86
	v_cmp_gt_f32_e32 vcc, s53, v86
	s_nop 1
	v_cndmask_b32_e32 v86, v86, v87, vcc
	v_rsq_f32_e32 v88, v86
	v_lshl_add_u64 v[86:87], v[82:83], 2, s[12:13]
	v_mul_f32_e32 v89, 0x45800000, v88
	v_cndmask_b32_e32 v88, v88, v89, vcc
	v_mul_f32_e32 v78, v78, v88
;   __device__ __forceinline__ void operator()(const acc8_t& acc, const pg8::Unit& u, int wr, int wc, int fr, int fq) const {
;     ...
; #pragma unroll
;     for (int ai = 0; ai < 2; ai++)
; #pragma unroll
;       for (int m = 0; m < 4; m++) {
;         const size_t token = EPI_TOKEN(u, ai, m);
;         const float rs = rsqrtf(rss[token] * (1.f / 1024.f) + 1e-6f);
; #pragma unroll
;         for (int bj = 0; bj < 2; bj++)
; #pragma unroll
;           for (int n = 0; n < 2; n++) {
;             const int f = EPI_COL(u, bj, n);
;             const float v0 = fmaxf(acc[ai][bj][m][n][0] * rs, 0.f), v1 = fmaxf(acc[ai][bj][m][n][1] * rs, 0.f);
;             const float v2 = fmaxf(acc[ai][bj][m][n][2] * rs, 0.f), v3 = fmaxf(acc[ai][bj][m][n][3] * rs, 0.f);
;             uint2 o; o.x = pack2(v0 * v0, v1 * v1); o.y = pack2(v2 * v2, v3 * v3);
;             *(uint2*)(H + token * 4096 + f) = o;
;           }
	v_mul_f32_e32 v79, v79, v88
	v_mul_f32_e32 v80, v80, v88
	v_mul_f32_e32 v81, v81, v88
	v_mul_f32_e32 v74, v74, v88
	v_mul_f32_e32 v75, v75, v88
	v_mul_f32_e32 v76, v76, v88
	v_mul_f32_e32 v77, v77, v88
	v_mul_f32_e32 v89, v70, v88
	v_mul_f32_e32 v90, v71, v88
	v_mul_f32_e32 v91, v72, v88
	v_mul_f32_e32 v92, v73, v88
	v_mul_f32_e32 v93, v66, v88
	v_mul_f32_e32 v94, v67, v88
	v_mul_f32_e32 v95, v68, v88
	v_mul_f32_e32 v88, v69, v88
	v_max_f32_e32 v66, 0, v78
	v_max_f32_e32 v67, 0, v79
	v_max_f32_e32 v68, 0, v80
	v_max_f32_e32 v69, 0, v81
	v_max_f32_e32 v70, 0, v74
	v_max_f32_e32 v71, 0, v75
	v_max_f32_e32 v72, 0, v76
	v_max_f32_e32 v73, 0, v77
	v_max_f32_e32 v74, 0, v89
	v_max_f32_e32 v75, 0, v90
	v_max_f32_e32 v76, 0, v91
	v_max_f32_e32 v77, 0, v92
	v_max_f32_e32 v78, 0, v93
	v_max_f32_e32 v79, 0, v94
	v_max_f32_e32 v80, 0, v95
	v_max_f32_e32 v81, 0, v88
	v_pk_mul_f32 v[66:67], v[66:67], v[66:67]
	v_pk_mul_f32 v[68:69], v[68:69], v[68:69]
	v_pk_mul_f32 v[70:71], v[70:71], v[70:71]
	v_pk_mul_f32 v[72:73], v[72:73], v[72:73]
	v_pk_mul_f32 v[74:75], v[74:75], v[74:75]
	v_pk_mul_f32 v[76:77], v[76:77], v[76:77]
	v_pk_mul_f32 v[78:79], v[78:79], v[78:79]
	v_pk_mul_f32 v[80:81], v[80:81], v[80:81]
	v_cvt_pk_bf16_f32 v66, v66, v67
	v_cvt_pk_bf16_f32 v67, v68, v69
	v_cvt_pk_bf16_f32 v68, v70, v71
	v_cvt_pk_bf16_f32 v69, v72, v73
	v_cvt_pk_bf16_f32 v70, v74, v75
	v_cvt_pk_bf16_f32 v71, v76, v77
	v_cvt_pk_bf16_f32 v72, v78, v79
	v_cvt_pk_bf16_f32 v73, v80, v81
	global_store_dwordx2 v[84:85], v[66:67], off
	global_store_dwordx2 v[84:85], v[68:69], off offset:32
	global_store_dwordx2 v[84:85], v[70:71], off offset:256
	global_store_dwordx2 v[84:85], v[72:73], off offset:288
	v_mov_b32_e32 v70, v179
	v_lshlrev_b64 v[68:69], 13, v[82:83]
	v_add_u32_e32 v66, 0x90, v140
	v_lshl_add_u64 v[68:69], s[10:11], 0, v[68:69]
	v_ashrrev_i32_e32 v67, 31, v66
	v_lshl_add_u64 v[68:69], v[68:69], 0, v[138:139]
	v_fmamk_f32 v70, v70, 0x3a800000, v161
	v_mul_f32_e32 v71, 0x4b800000, v70
	v_cmp_gt_f32_e32 vcc, s53, v70
	s_nop 1
	v_cndmask_b32_e32 v70, v70, v71, vcc
	v_rsq_f32_e32 v72, v70
	v_lshl_add_u64 v[70:71], v[66:67], 2, s[12:13]
	v_mul_f32_e32 v73, 0x45800000, v72
	v_cndmask_b32_e32 v72, v72, v73, vcc
	v_mul_f32_e32 v62, v62, v72
	v_mul_f32_e32 v63, v63, v72
	v_mul_f32_e32 v64, v64, v72
	v_mul_f32_e32 v65, v65, v72
	v_mul_f32_e32 v58, v58, v72
	v_mul_f32_e32 v59, v59, v72
	v_mul_f32_e32 v60, v60, v72
	v_mul_f32_e32 v61, v61, v72
	v_mul_f32_e32 v73, v54, v72
	v_mul_f32_e32 v74, v55, v72
	v_mul_f32_e32 v75, v56, v72
	v_mul_f32_e32 v76, v57, v72
	v_mul_f32_e32 v77, v50, v72
	v_mul_f32_e32 v78, v51, v72
	v_mul_f32_e32 v79, v52, v72
	v_mul_f32_e32 v72, v53, v72
	v_max_f32_e32 v50, 0, v62
	v_max_f32_e32 v51, 0, v63
	v_max_f32_e32 v52, 0, v64
	v_max_f32_e32 v53, 0, v65
	v_max_f32_e32 v54, 0, v58
	v_max_f32_e32 v55, 0, v59
	v_max_f32_e32 v56, 0, v60
	v_max_f32_e32 v57, 0, v61
	v_max_f32_e32 v58, 0, v73
	v_max_f32_e32 v59, 0, v74
	v_max_f32_e32 v60, 0, v75
	v_max_f32_e32 v61, 0, v76
	v_max_f32_e32 v62, 0, v77
	v_max_f32_e32 v63, 0, v78
	v_max_f32_e32 v64, 0, v79
	v_max_f32_e32 v65, 0, v72
	v_pk_mul_f32 v[50:51], v[50:51], v[50:51]
	v_pk_mul_f32 v[52:53], v[52:53], v[52:53]
	v_pk_mul_f32 v[54:55], v[54:55], v[54:55]
	v_pk_mul_f32 v[56:57], v[56:57], v[56:57]
	v_pk_mul_f32 v[58:59], v[58:59], v[58:59]
	v_pk_mul_f32 v[60:61], v[60:61], v[60:61]
	v_pk_mul_f32 v[62:63], v[62:63], v[62:63]
	v_pk_mul_f32 v[64:65], v[64:65], v[64:65]
	v_cvt_pk_bf16_f32 v50, v50, v51
	v_cvt_pk_bf16_f32 v51, v52, v53
	v_cvt_pk_bf16_f32 v52, v54, v55
	v_cvt_pk_bf16_f32 v53, v56, v57
	v_cvt_pk_bf16_f32 v54, v58, v59
	v_cvt_pk_bf16_f32 v55, v60, v61
	v_cvt_pk_bf16_f32 v56, v62, v63
	v_cvt_pk_bf16_f32 v57, v64, v65
	global_store_dwordx2 v[68:69], v[50:51], off
	global_store_dwordx2 v[68:69], v[52:53], off offset:32
	global_store_dwordx2 v[68:69], v[54:55], off offset:256
	global_store_dwordx2 v[68:69], v[56:57], off offset:288
	v_mov_b32_e32 v54, v180
	v_lshlrev_b64 v[52:53], 13, v[66:67]
	v_add_u32_e32 v50, 0xa0, v140
	v_lshl_add_u64 v[52:53], s[10:11], 0, v[52:53]
	v_ashrrev_i32_e32 v51, 31, v50
	v_lshl_add_u64 v[52:53], v[52:53], 0, v[138:139]
	v_fmamk_f32 v54, v54, 0x3a800000, v161
	v_mul_f32_e32 v55, 0x4b800000, v54
	v_cmp_gt_f32_e32 vcc, s53, v54
	s_nop 1
	v_cndmask_b32_e32 v54, v54, v55, vcc
	v_rsq_f32_e32 v56, v54
	v_lshl_add_u64 v[54:55], v[50:51], 2, s[12:13]
	v_mul_f32_e32 v57, 0x45800000, v56
	v_cndmask_b32_e32 v56, v56, v57, vcc
	v_mul_f32_e32 v46, v46, v56
	v_mul_f32_e32 v47, v47, v56
	v_mul_f32_e32 v48, v48, v56
	v_mul_f32_e32 v49, v49, v56
	v_mul_f32_e32 v42, v42, v56
	v_mul_f32_e32 v43, v43, v56
	v_mul_f32_e32 v44, v44, v56
	v_mul_f32_e32 v45, v45, v56
	v_mul_f32_e32 v57, v38, v56
	v_mul_f32_e32 v58, v39, v56
	v_mul_f32_e32 v59, v40, v56
	v_mul_f32_e32 v60, v41, v56
	v_mul_f32_e32 v61, v34, v56
	v_mul_f32_e32 v62, v35, v56
	v_mul_f32_e32 v63, v36, v56
	v_mul_f32_e32 v56, v37, v56
	v_max_f32_e32 v34, 0, v46
	v_max_f32_e32 v35, 0, v47
	v_max_f32_e32 v36, 0, v48
	v_max_f32_e32 v37, 0, v49
	v_max_f32_e32 v38, 0, v42
	v_max_f32_e32 v39, 0, v43
	v_max_f32_e32 v40, 0, v44
	v_max_f32_e32 v41, 0, v45
	v_max_f32_e32 v42, 0, v57
	v_max_f32_e32 v43, 0, v58
	v_max_f32_e32 v44, 0, v59
	v_max_f32_e32 v45, 0, v60
	v_max_f32_e32 v46, 0, v61
	v_max_f32_e32 v47, 0, v62
	v_max_f32_e32 v48, 0, v63
;   __device__ __forceinline__ void operator()(const acc8_t& acc, const pg8::Unit& u, int wr, int wc, int fr, int fq) const {
;     ...
; #pragma unroll
;     for (int ai = 0; ai < 2; ai++)
; #pragma unroll
;       for (int m = 0; m < 4; m++) {
;         const size_t token = EPI_TOKEN(u, ai, m);
;         const float rs = rsqrtf(rss[token] * (1.f / 1024.f) + 1e-6f);
; #pragma unroll
;         for (int bj = 0; bj < 2; bj++)
; #pragma unroll
;           for (int n = 0; n < 2; n++) {
;             const int f = EPI_COL(u, bj, n);
;             const float v0 = fmaxf(acc[ai][bj][m][n][0] * rs, 0.f), v1 = fmaxf(acc[ai][bj][m][n][1] * rs, 0.f);
;             const float v2 = fmaxf(acc[ai][bj][m][n][2] * rs, 0.f), v3 = fmaxf(acc[ai][bj][m][n][3] * rs, 0.f);
;             uint2 o; o.x = pack2(v0 * v0, v1 * v1); o.y = pack2(v2 * v2, v3 * v3);
;             *(uint2*)(H + token * 4096 + f) = o;
;           }
	v_max_f32_e32 v49, 0, v56
	v_pk_mul_f32 v[34:35], v[34:35], v[34:35]
	v_pk_mul_f32 v[36:37], v[36:37], v[36:37]
	v_pk_mul_f32 v[38:39], v[38:39], v[38:39]
	v_pk_mul_f32 v[40:41], v[40:41], v[40:41]
	v_pk_mul_f32 v[42:43], v[42:43], v[42:43]
	v_pk_mul_f32 v[44:45], v[44:45], v[44:45]
	v_pk_mul_f32 v[46:47], v[46:47], v[46:47]
	v_pk_mul_f32 v[48:49], v[48:49], v[48:49]
	v_cvt_pk_bf16_f32 v34, v34, v35
	v_cvt_pk_bf16_f32 v35, v36, v37
	v_cvt_pk_bf16_f32 v36, v38, v39
	v_cvt_pk_bf16_f32 v37, v40, v41
	v_cvt_pk_bf16_f32 v38, v42, v43
	v_cvt_pk_bf16_f32 v39, v44, v45
	v_cvt_pk_bf16_f32 v40, v46, v47
	v_cvt_pk_bf16_f32 v41, v48, v49
	global_store_dwordx2 v[52:53], v[34:35], off
	global_store_dwordx2 v[52:53], v[36:37], off offset:32
	global_store_dwordx2 v[52:53], v[38:39], off offset:256
	global_store_dwordx2 v[52:53], v[40:41], off offset:288
	v_mov_b32_e32 v38, v181
	v_lshlrev_b64 v[36:37], 13, v[50:51]
	v_add_u32_e32 v34, 0xb0, v140
	v_lshl_add_u64 v[36:37], s[10:11], 0, v[36:37]
	v_ashrrev_i32_e32 v35, 31, v34
	v_lshl_add_u64 v[36:37], v[36:37], 0, v[138:139]
	v_fmamk_f32 v38, v38, 0x3a800000, v161
	v_mul_f32_e32 v39, 0x4b800000, v38
	v_cmp_gt_f32_e32 vcc, s53, v38
	s_nop 1
	v_cndmask_b32_e32 v38, v38, v39, vcc
	v_rsq_f32_e32 v40, v38
	v_lshl_add_u64 v[38:39], v[34:35], 2, s[12:13]
	v_mul_f32_e32 v41, 0x45800000, v40
	v_cndmask_b32_e32 v40, v40, v41, vcc
	v_mul_f32_e32 v30, v30, v40
	v_mul_f32_e32 v31, v31, v40
	v_mul_f32_e32 v32, v32, v40
	v_mul_f32_e32 v33, v33, v40
	v_mul_f32_e32 v26, v26, v40
	v_mul_f32_e32 v27, v27, v40
	v_mul_f32_e32 v28, v28, v40
	v_mul_f32_e32 v29, v29, v40
	v_mul_f32_e32 v41, v22, v40
	v_mul_f32_e32 v42, v23, v40
	v_mul_f32_e32 v43, v24, v40
	v_mul_f32_e32 v44, v25, v40
	v_mul_f32_e32 v45, v18, v40
	v_mul_f32_e32 v46, v19, v40
	v_mul_f32_e32 v47, v20, v40
	v_mul_f32_e32 v40, v21, v40
	v_max_f32_e32 v18, 0, v30
	v_max_f32_e32 v19, 0, v31
	v_max_f32_e32 v20, 0, v32
	v_max_f32_e32 v21, 0, v33
	v_max_f32_e32 v22, 0, v26
	v_max_f32_e32 v23, 0, v27
	v_max_f32_e32 v24, 0, v28
	v_max_f32_e32 v25, 0, v29
	v_max_f32_e32 v26, 0, v41
	v_max_f32_e32 v27, 0, v42
	v_max_f32_e32 v28, 0, v43
	v_max_f32_e32 v29, 0, v44
	v_max_f32_e32 v30, 0, v45
	v_max_f32_e32 v31, 0, v46
	v_max_f32_e32 v32, 0, v47
	v_max_f32_e32 v33, 0, v40
	v_pk_mul_f32 v[18:19], v[18:19], v[18:19]
	v_pk_mul_f32 v[20:21], v[20:21], v[20:21]
	v_pk_mul_f32 v[22:23], v[22:23], v[22:23]
	v_pk_mul_f32 v[24:25], v[24:25], v[24:25]
	v_pk_mul_f32 v[26:27], v[26:27], v[26:27]
	v_pk_mul_f32 v[28:29], v[28:29], v[28:29]
	v_pk_mul_f32 v[30:31], v[30:31], v[30:31]
	v_pk_mul_f32 v[32:33], v[32:33], v[32:33]
	v_cvt_pk_bf16_f32 v18, v18, v19
	v_cvt_pk_bf16_f32 v19, v20, v21
	v_cvt_pk_bf16_f32 v20, v22, v23
	v_cvt_pk_bf16_f32 v21, v24, v25
	v_cvt_pk_bf16_f32 v22, v26, v27
	v_cvt_pk_bf16_f32 v23, v28, v29
	v_cvt_pk_bf16_f32 v24, v30, v31
	v_cvt_pk_bf16_f32 v25, v32, v33
	global_store_dwordx2 v[36:37], v[18:19], off
	global_store_dwordx2 v[36:37], v[20:21], off offset:32
	global_store_dwordx2 v[36:37], v[22:23], off offset:256
	global_store_dwordx2 v[36:37], v[24:25], off offset:288
	v_mov_b32_e32 v18, v182
	s_and_b64 vcc, exec, s[4:5]
	v_fmamk_f32 v18, v18, 0x3a800000, v161
	v_mul_f32_e32 v19, 0x4b800000, v18
	v_cmp_gt_f32_e64 s[4:5], s53, v18
	s_nop 1
	v_cndmask_b32_e64 v18, v18, v19, s[4:5]
	v_rsq_f32_e32 v20, v18
	v_lshlrev_b64 v[18:19], 13, v[34:35]
	v_lshl_add_u64 v[18:19], s[10:11], 0, v[18:19]
	v_lshl_add_u64 v[18:19], v[18:19], 0, v[138:139]
	v_mul_f32_e32 v21, 0x45800000, v20
	v_cndmask_b32_e64 v20, v20, v21, s[4:5]
	v_mul_f32_e32 v14, v14, v20
	v_mul_f32_e32 v15, v15, v20
	v_mul_f32_e32 v16, v16, v20
	v_mul_f32_e32 v17, v17, v20
	v_mul_f32_e32 v10, v10, v20
	v_mul_f32_e32 v11, v11, v20
	v_mul_f32_e32 v12, v12, v20
	v_mul_f32_e32 v13, v13, v20
	v_mul_f32_e32 v21, v6, v20
	v_mul_f32_e32 v22, v7, v20
	v_mul_f32_e32 v23, v8, v20
	v_mul_f32_e32 v24, v9, v20
	v_mul_f32_e32 v25, v2, v20
	v_mul_f32_e32 v26, v3, v20
	v_mul_f32_e32 v27, v4, v20
	v_mul_f32_e32 v20, v5, v20
	v_max_f32_e32 v2, 0, v14
	v_max_f32_e32 v3, 0, v15
	v_max_f32_e32 v4, 0, v16
	v_max_f32_e32 v5, 0, v17
	v_max_f32_e32 v6, 0, v10
	v_max_f32_e32 v7, 0, v11
	v_max_f32_e32 v8, 0, v12
	v_max_f32_e32 v9, 0, v13
	v_max_f32_e32 v10, 0, v21
	v_max_f32_e32 v11, 0, v22
	v_max_f32_e32 v12, 0, v23
	v_max_f32_e32 v13, 0, v24
	v_max_f32_e32 v14, 0, v25
	v_max_f32_e32 v15, 0, v26
	v_max_f32_e32 v16, 0, v27
	v_max_f32_e32 v17, 0, v20
	v_pk_mul_f32 v[2:3], v[2:3], v[2:3]
	v_pk_mul_f32 v[4:5], v[4:5], v[4:5]
	v_pk_mul_f32 v[6:7], v[6:7], v[6:7]
	v_pk_mul_f32 v[8:9], v[8:9], v[8:9]
	v_pk_mul_f32 v[10:11], v[10:11], v[10:11]
	v_pk_mul_f32 v[12:13], v[12:13], v[12:13]
	v_pk_mul_f32 v[14:15], v[14:15], v[14:15]
	v_pk_mul_f32 v[16:17], v[16:17], v[16:17]
	v_cvt_pk_bf16_f32 v2, v2, v3
	v_cvt_pk_bf16_f32 v3, v4, v5
	v_cvt_pk_bf16_f32 v4, v6, v7
	v_cvt_pk_bf16_f32 v5, v8, v9
	v_cvt_pk_bf16_f32 v6, v10, v11
	v_cvt_pk_bf16_f32 v7, v12, v13
	v_cvt_pk_bf16_f32 v8, v14, v15
	v_cvt_pk_bf16_f32 v9, v16, v17
	global_store_dwordx2 v[18:19], v[2:3], off
	global_store_dwordx2 v[18:19], v[4:5], off offset:32
	global_store_dwordx2 v[18:19], v[6:7], off offset:256
	global_store_dwordx2 v[18:19], v[8:9], off offset:288
	s_cbranch_vccz .LBB0_794
	s_waitcnt vmcnt(0)
	s_cmpk_gt_u32 s33, 0xff
	s_cbranch_scc1 .LBB0_804
	s_barrier
